# Y (gate/up) and X1B (out-proj) epilogue stores marked sc1 (write-through at agent scope) so the grid barrier's L2 write-back has less dirty data
# baseline (speedup 1.0000x reference)
; #define LAS __attribute__((address_space(3)))
; DI u32x2 pk4(f32x4 v) { u32x2 r; r.x = pk2(v[0], v[1]); r.y = pk2(v[2], v[3]); return r; }
;     DI void operator()(const AccT& acc, const Unit& u, int wr, int wc, int fr, int fq, LAS unsigned char* ldsx) const {
;     ...
;                 if (prompt) {
;                     if (ai | wr) { const int sai = wr ? ai : ai - 1, swr = wr ^ 1; const LAS float* hp = H + ((sai * 2 + swr) * 4 + wc) * 64 + 16 * n + 4 * fq;
;                         hm2 = *(const LAS f32x4*)hp; hm1 = *(const LAS f32x4*)(hp + 32); }
;                 } else { hm2 = *(const f32x4*)(state + (size_t)(sb * 2) * DFF + f); hm1 = *(const f32x4*)(state + (size_t)(sb * 2 + 1) * DFF + f); }
;                 f32x4 p1 = hm1, p2;
; #pragma unroll
;                 for (int j = 0; j < 4; ++j) p2[j] = fr == 1 ? hm1[j] : hm2[j];
; #pragma unroll
;                 for (int m = 0; m < 4; ++m) {
;                     const f32x4 g = acc[ai][0][m][n] * rs[ai][m];
;                     f32x4 gm1, gm2;
; #pragma unroll
;                     for (int j = 0; j < 4; ++j) {
;                         gm1[j] = __int_as_float(__builtin_amdgcn_update_dpp(__float_as_int(p1[j]), __float_as_int(g[j]), 0x111, 0xf, 0xf, false));
;                         gm2[j] = __int_as_float(__builtin_amdgcn_update_dpp(__float_as_int(p2[j]), __float_as_int(g[j]), 0x112, 0xf, 0xf, false));
;                         if (m < 3) {
;                             p1[j] = __int_as_float(__builtin_amdgcn_update_dpp(0, __float_as_int(g[j]), 0x121, 0xf, 0xf, false));
;                             p2[j] = __int_as_float(__builtin_amdgcn_update_dpp(0, __float_as_int(g[j]), 0x122, 0xf, 0xf, false)); }
;                     }
;                     const f32x4 cv = cb[n] + w0[n] * gm2 + w1[n] * gm1 + w2[n] * g;
;                     const f32x4 up = acc[ai][1][m][n] * rs[ai][m];
;                     f32x4 y;
; #pragma unroll
;                     for (int j = 0; j < 4; ++j) y[j] = cv[j] * __builtin_amdgcn_rcpf(1.f + __builtin_amdgcn_exp2f(-cv[j] * LOG2E)) * up[j];
;                     const int tok = tok0 + 128 * ai + 16 * m;
;                     bool ok = true;
;                     if (prompt && ai == 0 && m == 0) ok = (64 * wr + fr) >= 2;
;                     if (lastT) ok = ok && tok < SEQ;
;                     if (ok) *(u32x2*)(Y + ((unsigned)tok * (unsigned)DFF + (unsigned)f)) = pk4(y);
.Lgu_samp0:
	v_add_u32_e32 v213, 16, v172
	s_add_u32 s46, s54, 0xfffea000
	s_addc_u32 s47, s55, -1
	v_mul_lo_u32 v213, v213, s87
	v_cndmask_b32_e64 v160, 0, v124, s[94:95]
	v_cndmask_b32_e64 v124, v124, 0, s[94:95]
	v_cndmask_b32_e64 v164, 0, v132, s[96:97]
	v_cndmask_b32_e64 v132, v132, 0, s[96:97]
	v_cndmask_b32_e64 v161, 0, v125, s[94:95]
	v_cndmask_b32_e64 v125, v125, 0, s[94:95]
	v_cndmask_b32_e64 v165, 0, v133, s[96:97]
	v_cndmask_b32_e64 v133, v133, 0, s[96:97]
	v_cndmask_b32_e64 v162, 0, v126, s[94:95]
	v_cndmask_b32_e64 v126, v126, 0, s[94:95]
	v_cndmask_b32_e64 v166, 0, v134, s[96:97]
	v_cndmask_b32_e64 v134, v134, 0, s[96:97]
	v_cndmask_b32_e64 v163, 0, v127, s[94:95]
	v_cndmask_b32_e64 v127, v127, 0, s[94:95]
	v_cndmask_b32_e64 v167, 0, v135, s[96:97]
	v_cndmask_b32_e64 v135, v135, 0, s[96:97]
	v_add_lshl_u32 v213, v213, v216, 1
	v_pk_mul_f32 v[156:157], v[156:157], v[214:215] op_sel_hi:[1,0]
	v_pk_mul_f32 v[158:159], v[158:159], v[214:215] op_sel_hi:[1,0]
	v_pk_mul_f32 v[152:153], v[152:153], v[214:215] op_sel_hi:[1,0]
	v_pk_mul_f32 v[154:155], v[154:155], v[214:215] op_sel_hi:[1,0]
	v_pk_fma_f32 v[218:219], v[128:129], v[156:157], v[136:137]
	v_pk_fma_f32 v[220:221], v[130:131], v[158:159], v[138:139]
	v_fmac_f32_dpp v218, v156, v124 row_ror:1 row_mask:0xf bank_mask:0xf
	v_fmac_f32_dpp v219, v157, v125 row_ror:1 row_mask:0xf bank_mask:0xf
	v_fmac_f32_dpp v220, v158, v126 row_ror:1 row_mask:0xf bank_mask:0xf
	v_fmac_f32_dpp v221, v159, v127 row_ror:1 row_mask:0xf bank_mask:0xf
	v_fmac_f32_dpp v218, v156, v132 row_ror:2 row_mask:0xf bank_mask:0xf
	v_fmac_f32_dpp v219, v157, v133 row_ror:2 row_mask:0xf bank_mask:0xf
	v_fmac_f32_dpp v220, v158, v134 row_ror:2 row_mask:0xf bank_mask:0xf
	v_fmac_f32_dpp v221, v159, v135 row_ror:2 row_mask:0xf bank_mask:0xf
	s_waitcnt lgkmcnt(0)
	v_fmac_f32_e32 v218, v248, v160
	v_fmac_f32_e32 v219, v249, v161
	v_fmac_f32_e32 v220, v250, v162
	v_fmac_f32_e32 v221, v251, v163
	v_fmac_f32_dpp v218, v248, v164 row_ror:14 row_mask:0xf bank_mask:0xf
	v_fmac_f32_dpp v219, v249, v165 row_ror:14 row_mask:0xf bank_mask:0xf
	v_fmac_f32_dpp v220, v250, v166 row_ror:14 row_mask:0xf bank_mask:0xf
	v_fmac_f32_dpp v221, v251, v167 row_ror:14 row_mask:0xf bank_mask:0xf
	v_pk_mul_f32 v[204:205], v[218:219], v[184:185] op_sel:[0,1] op_sel_hi:[1,1]
	v_pk_mul_f32 v[148:149], v[148:149], v[210:211] op_sel_hi:[1,0]
	v_pk_mul_f32 v[206:207], v[220:221], v[184:185] op_sel:[0,1] op_sel_hi:[1,1]
	v_pk_mul_f32 v[150:151], v[150:151], v[210:211] op_sel_hi:[1,0]
	v_exp_f32_e32 v204, v204
	v_pk_mul_f32 v[144:145], v[144:145], v[210:211] op_sel_hi:[1,0]
	v_exp_f32_e32 v205, v205
	v_pk_mul_f32 v[146:147], v[146:147], v[210:211] op_sel_hi:[1,0]
	v_exp_f32_e32 v206, v206
	v_pk_fma_f32 v[222:223], v[128:129], v[148:149], v[136:137]
	v_exp_f32_e32 v207, v207
	v_pk_fma_f32 v[224:225], v[130:131], v[150:151], v[138:139]
	v_pk_add_f32 v[204:205], v[204:205], 1.0 op_sel_hi:[1,0]
	v_fmac_f32_dpp v222, v148, v124 row_ror:1 row_mask:0xf bank_mask:0xf
	v_pk_add_f32 v[206:207], v[206:207], 1.0 op_sel_hi:[1,0]
	v_fmac_f32_dpp v223, v149, v125 row_ror:1 row_mask:0xf bank_mask:0xf
	v_rcp_f32_e32 v204, v204
	v_fmac_f32_dpp v224, v150, v126 row_ror:1 row_mask:0xf bank_mask:0xf
	v_rcp_f32_e32 v205, v205
	v_fmac_f32_dpp v225, v151, v127 row_ror:1 row_mask:0xf bank_mask:0xf
	v_rcp_f32_e32 v206, v206
	v_fmac_f32_dpp v222, v148, v132 row_ror:2 row_mask:0xf bank_mask:0xf
	v_rcp_f32_e32 v207, v207
	v_fmac_f32_dpp v223, v149, v133 row_ror:2 row_mask:0xf bank_mask:0xf
	v_pk_mul_f32 v[218:219], v[218:219], v[204:205]
	v_fmac_f32_dpp v224, v150, v134 row_ror:2 row_mask:0xf bank_mask:0xf
	v_pk_mul_f32 v[220:221], v[220:221], v[206:207]
	v_fmac_f32_dpp v225, v151, v135 row_ror:2 row_mask:0xf bank_mask:0xf
	v_pk_mul_f32 v[152:153], v[152:153], v[218:219]
	v_fmac_f32_dpp v222, v156, v160 row_ror:1 row_mask:0xf bank_mask:0xf
	v_pk_mul_f32 v[154:155], v[154:155], v[220:221]
	v_fmac_f32_dpp v223, v157, v161 row_ror:1 row_mask:0xf bank_mask:0xf
	v_cvt_pk_bf16_f32 v152, v152, v153
	v_fmac_f32_dpp v224, v158, v162 row_ror:1 row_mask:0xf bank_mask:0xf
	v_cvt_pk_bf16_f32 v153, v154, v155
	v_fmac_f32_dpp v225, v159, v163 row_ror:1 row_mask:0xf bank_mask:0xf
	v_fmac_f32_dpp v222, v156, v164 row_ror:2 row_mask:0xf bank_mask:0xf
	v_fmac_f32_dpp v223, v157, v165 row_ror:2 row_mask:0xf bank_mask:0xf
	v_fmac_f32_dpp v224, v158, v166 row_ror:2 row_mask:0xf bank_mask:0xf
	v_fmac_f32_dpp v225, v159, v167 row_ror:2 row_mask:0xf bank_mask:0xf
	s_and_saveexec_b64 s[28:29], s[60:61]
	global_store_dwordx2 v213, v[152:153], s[46:47] sc1
	s_mov_b64 exec, s[28:29]
	s_add_u32 s46, s46, 0x16000
	s_addc_u32 s47, s47, 0
	v_pk_mul_f32 v[204:205], v[222:223], v[184:185] op_sel:[0,1] op_sel_hi:[1,1]
	v_pk_mul_f32 v[140:141], v[140:141], v[208:209] op_sel_hi:[1,0]
	v_pk_mul_f32 v[206:207], v[224:225], v[184:185] op_sel:[0,1] op_sel_hi:[1,1]
	v_pk_mul_f32 v[142:143], v[142:143], v[208:209] op_sel_hi:[1,0]
	v_exp_f32_e32 v204, v204
	v_pk_mul_f32 v[120:121], v[120:121], v[208:209] op_sel_hi:[1,0]
	v_exp_f32_e32 v205, v205
	v_pk_mul_f32 v[122:123], v[122:123], v[208:209] op_sel_hi:[1,0]
	v_exp_f32_e32 v206, v206
	v_pk_fma_f32 v[218:219], v[128:129], v[140:141], v[136:137]
	v_exp_f32_e32 v207, v207
	v_pk_fma_f32 v[220:221], v[130:131], v[142:143], v[138:139]
	v_pk_add_f32 v[204:205], v[204:205], 1.0 op_sel_hi:[1,0]
	v_fmac_f32_dpp v218, v140, v124 row_ror:1 row_mask:0xf bank_mask:0xf
	v_pk_add_f32 v[206:207], v[206:207], 1.0 op_sel_hi:[1,0]
	v_fmac_f32_dpp v219, v141, v125 row_ror:1 row_mask:0xf bank_mask:0xf
	v_rcp_f32_e32 v204, v204
	v_fmac_f32_dpp v220, v142, v126 row_ror:1 row_mask:0xf bank_mask:0xf
; #define LAS __attribute__((address_space(3)))
; DI u32x2 pk4(f32x4 v) { u32x2 r; r.x = pk2(v[0], v[1]); r.y = pk2(v[2], v[3]); return r; }
;     DI void operator()(const AccT& acc, const Unit& u, int wr, int wc, int fr, int fq, LAS unsigned char* ldsx) const {
;     ...
;                 if (prompt) {
;                     if (ai | wr) { const int sai = wr ? ai : ai - 1, swr = wr ^ 1; const LAS float* hp = H + ((sai * 2 + swr) * 4 + wc) * 64 + 16 * n + 4 * fq;
;                         hm2 = *(const LAS f32x4*)hp; hm1 = *(const LAS f32x4*)(hp + 32); }
;                 } else { hm2 = *(const f32x4*)(state + (size_t)(sb * 2) * DFF + f); hm1 = *(const f32x4*)(state + (size_t)(sb * 2 + 1) * DFF + f); }
;                 f32x4 p1 = hm1, p2;
; #pragma unroll
;                 for (int j = 0; j < 4; ++j) p2[j] = fr == 1 ? hm1[j] : hm2[j];
; #pragma unroll
;                 for (int m = 0; m < 4; ++m) {
;                     const f32x4 g = acc[ai][0][m][n] * rs[ai][m];
;                     f32x4 gm1, gm2;
; #pragma unroll
;                     for (int j = 0; j < 4; ++j) {
;                         gm1[j] = __int_as_float(__builtin_amdgcn_update_dpp(__float_as_int(p1[j]), __float_as_int(g[j]), 0x111, 0xf, 0xf, false));
;                         gm2[j] = __int_as_float(__builtin_amdgcn_update_dpp(__float_as_int(p2[j]), __float_as_int(g[j]), 0x112, 0xf, 0xf, false));
;                         if (m < 3) {
;                             p1[j] = __int_as_float(__builtin_amdgcn_update_dpp(0, __float_as_int(g[j]), 0x121, 0xf, 0xf, false));
;                             p2[j] = __int_as_float(__builtin_amdgcn_update_dpp(0, __float_as_int(g[j]), 0x122, 0xf, 0xf, false)); }
;                     }
;                     const f32x4 cv = cb[n] + w0[n] * gm2 + w1[n] * gm1 + w2[n] * g;
;                     const f32x4 up = acc[ai][1][m][n] * rs[ai][m];
;                     f32x4 y;
; #pragma unroll
;                     for (int j = 0; j < 4; ++j) y[j] = cv[j] * __builtin_amdgcn_rcpf(1.f + __builtin_amdgcn_exp2f(-cv[j] * LOG2E)) * up[j];
;                     const int tok = tok0 + 128 * ai + 16 * m;
;                     bool ok = true;
;                     if (prompt && ai == 0 && m == 0) ok = (64 * wr + fr) >= 2;
;                     if (lastT) ok = ok && tok < SEQ;
;                     if (ok) *(u32x2*)(Y + ((unsigned)tok * (unsigned)DFF + (unsigned)f)) = pk4(y);
	v_rcp_f32_e32 v205, v205
	v_fmac_f32_dpp v221, v143, v127 row_ror:1 row_mask:0xf bank_mask:0xf
	v_rcp_f32_e32 v206, v206
	v_fmac_f32_dpp v218, v140, v132 row_ror:2 row_mask:0xf bank_mask:0xf
	v_rcp_f32_e32 v207, v207
	v_fmac_f32_dpp v219, v141, v133 row_ror:2 row_mask:0xf bank_mask:0xf
	v_pk_mul_f32 v[222:223], v[222:223], v[204:205]
	v_fmac_f32_dpp v220, v142, v134 row_ror:2 row_mask:0xf bank_mask:0xf
	v_pk_mul_f32 v[224:225], v[224:225], v[206:207]
	v_fmac_f32_dpp v221, v143, v135 row_ror:2 row_mask:0xf bank_mask:0xf
	v_pk_mul_f32 v[144:145], v[144:145], v[222:223]
	v_fmac_f32_dpp v218, v148, v160 row_ror:1 row_mask:0xf bank_mask:0xf
	v_pk_mul_f32 v[146:147], v[146:147], v[224:225]
	v_fmac_f32_dpp v219, v149, v161 row_ror:1 row_mask:0xf bank_mask:0xf
	v_cvt_pk_bf16_f32 v144, v144, v145
	v_fmac_f32_dpp v220, v150, v162 row_ror:1 row_mask:0xf bank_mask:0xf
	v_cvt_pk_bf16_f32 v145, v146, v147
	v_fmac_f32_dpp v221, v151, v163 row_ror:1 row_mask:0xf bank_mask:0xf
	v_fmac_f32_dpp v218, v148, v164 row_ror:2 row_mask:0xf bank_mask:0xf
	v_fmac_f32_dpp v219, v149, v165 row_ror:2 row_mask:0xf bank_mask:0xf
	v_fmac_f32_dpp v220, v150, v166 row_ror:2 row_mask:0xf bank_mask:0xf
	v_fmac_f32_dpp v221, v151, v167 row_ror:2 row_mask:0xf bank_mask:0xf
	s_and_saveexec_b64 s[28:29], s[62:63]
	global_store_dwordx2 v213, v[144:145], s[46:47] sc1
	s_mov_b64 exec, s[28:29]
	s_add_u32 s46, s46, 0x16000
	s_addc_u32 s47, s47, 0
	v_pk_mul_f32 v[204:205], v[218:219], v[184:185] op_sel:[0,1] op_sel_hi:[1,1]
	v_pk_mul_f32 v[116:117], v[116:117], v[202:203] op_sel_hi:[1,0]
	v_pk_mul_f32 v[206:207], v[220:221], v[184:185] op_sel:[0,1] op_sel_hi:[1,1]
	v_pk_mul_f32 v[118:119], v[118:119], v[202:203] op_sel_hi:[1,0]
	v_exp_f32_e32 v204, v204
	v_pk_mul_f32 v[112:113], v[112:113], v[202:203] op_sel_hi:[1,0]
	v_exp_f32_e32 v205, v205
	v_pk_mul_f32 v[114:115], v[114:115], v[202:203] op_sel_hi:[1,0]
	v_exp_f32_e32 v206, v206
	v_pk_fma_f32 v[222:223], v[128:129], v[116:117], v[136:137]
	v_exp_f32_e32 v207, v207
	v_pk_fma_f32 v[224:225], v[130:131], v[118:119], v[138:139]
	v_pk_add_f32 v[204:205], v[204:205], 1.0 op_sel_hi:[1,0]
	v_fmac_f32_dpp v222, v116, v124 row_ror:1 row_mask:0xf bank_mask:0xf
	v_pk_add_f32 v[206:207], v[206:207], 1.0 op_sel_hi:[1,0]
	v_fmac_f32_dpp v223, v117, v125 row_ror:1 row_mask:0xf bank_mask:0xf
	v_rcp_f32_e32 v204, v204
	v_fmac_f32_dpp v224, v118, v126 row_ror:1 row_mask:0xf bank_mask:0xf
	v_rcp_f32_e32 v205, v205
	v_fmac_f32_dpp v225, v119, v127 row_ror:1 row_mask:0xf bank_mask:0xf
	v_rcp_f32_e32 v206, v206
	v_fmac_f32_dpp v222, v116, v132 row_ror:2 row_mask:0xf bank_mask:0xf
	v_rcp_f32_e32 v207, v207
	v_fmac_f32_dpp v223, v117, v133 row_ror:2 row_mask:0xf bank_mask:0xf
	v_pk_mul_f32 v[218:219], v[218:219], v[204:205]
	v_fmac_f32_dpp v224, v118, v134 row_ror:2 row_mask:0xf bank_mask:0xf
	v_pk_mul_f32 v[220:221], v[220:221], v[206:207]
	v_fmac_f32_dpp v225, v119, v135 row_ror:2 row_mask:0xf bank_mask:0xf
	v_pk_mul_f32 v[120:121], v[120:121], v[218:219]
	v_fmac_f32_dpp v222, v140, v160 row_ror:1 row_mask:0xf bank_mask:0xf
	v_pk_mul_f32 v[122:123], v[122:123], v[220:221]
	v_fmac_f32_dpp v223, v141, v161 row_ror:1 row_mask:0xf bank_mask:0xf
	v_cvt_pk_bf16_f32 v120, v120, v121
	v_fmac_f32_dpp v224, v142, v162 row_ror:1 row_mask:0xf bank_mask:0xf
	v_cvt_pk_bf16_f32 v121, v122, v123
	v_fmac_f32_dpp v225, v143, v163 row_ror:1 row_mask:0xf bank_mask:0xf
	v_fmac_f32_dpp v222, v140, v164 row_ror:2 row_mask:0xf bank_mask:0xf
	v_fmac_f32_dpp v223, v141, v165 row_ror:2 row_mask:0xf bank_mask:0xf
	v_fmac_f32_dpp v224, v142, v166 row_ror:2 row_mask:0xf bank_mask:0xf
	v_fmac_f32_dpp v225, v143, v167 row_ror:2 row_mask:0xf bank_mask:0xf
	s_and_saveexec_b64 s[28:29], s[64:65]
	global_store_dwordx2 v213, v[120:121], s[46:47] sc1
	s_mov_b64 exec, s[28:29]
	s_add_u32 s46, s46, 0x16000
	s_addc_u32 s47, s47, 0
	v_pk_mul_f32 v[204:205], v[222:223], v[184:185] op_sel:[0,1] op_sel_hi:[1,1]
	v_pk_mul_f32 v[108:109], v[108:109], v[200:201] op_sel_hi:[1,0]
	v_pk_mul_f32 v[206:207], v[224:225], v[184:185] op_sel:[0,1] op_sel_hi:[1,1]
	v_pk_mul_f32 v[110:111], v[110:111], v[200:201] op_sel_hi:[1,0]
	v_exp_f32_e32 v204, v204
	v_pk_mul_f32 v[104:105], v[104:105], v[200:201] op_sel_hi:[1,0]
	v_exp_f32_e32 v205, v205
	v_pk_mul_f32 v[106:107], v[106:107], v[200:201] op_sel_hi:[1,0]
	v_exp_f32_e32 v206, v206
	v_pk_fma_f32 v[218:219], v[128:129], v[108:109], v[136:137]
	v_exp_f32_e32 v207, v207
	v_pk_fma_f32 v[220:221], v[130:131], v[110:111], v[138:139]
	v_pk_add_f32 v[204:205], v[204:205], 1.0 op_sel_hi:[1,0]
	v_fmac_f32_dpp v218, v108, v124 row_ror:1 row_mask:0xf bank_mask:0xf
	v_pk_add_f32 v[206:207], v[206:207], 1.0 op_sel_hi:[1,0]
	v_fmac_f32_dpp v219, v109, v125 row_ror:1 row_mask:0xf bank_mask:0xf
	v_rcp_f32_e32 v204, v204
	v_fmac_f32_dpp v220, v110, v126 row_ror:1 row_mask:0xf bank_mask:0xf
	v_rcp_f32_e32 v205, v205
	v_fmac_f32_dpp v221, v111, v127 row_ror:1 row_mask:0xf bank_mask:0xf
	v_rcp_f32_e32 v206, v206
	v_fmac_f32_dpp v218, v108, v132 row_ror:2 row_mask:0xf bank_mask:0xf
	v_rcp_f32_e32 v207, v207
	v_fmac_f32_dpp v219, v109, v133 row_ror:2 row_mask:0xf bank_mask:0xf
	v_pk_mul_f32 v[222:223], v[222:223], v[204:205]
	v_fmac_f32_dpp v220, v110, v134 row_ror:2 row_mask:0xf bank_mask:0xf
	v_pk_mul_f32 v[224:225], v[224:225], v[206:207]
	v_fmac_f32_dpp v221, v111, v135 row_ror:2 row_mask:0xf bank_mask:0xf
	v_pk_mul_f32 v[112:113], v[112:113], v[222:223]
	v_fmac_f32_dpp v218, v248, v160 row_ror:12 row_mask:0xf bank_mask:0xf
	v_pk_mul_f32 v[114:115], v[114:115], v[224:225]
	v_fmac_f32_dpp v219, v249, v161 row_ror:12 row_mask:0xf bank_mask:0xf
	v_cvt_pk_bf16_f32 v112, v112, v113
; #define LAS __attribute__((address_space(3)))
; DI u32x2 pk4(f32x4 v) { u32x2 r; r.x = pk2(v[0], v[1]); r.y = pk2(v[2], v[3]); return r; }
;     DI void operator()(const AccT& acc, const Unit& u, int wr, int wc, int fr, int fq, LAS unsigned char* ldsx) const {
;     ...
;                 if (prompt) {
;                     if (ai | wr) { const int sai = wr ? ai : ai - 1, swr = wr ^ 1; const LAS float* hp = H + ((sai * 2 + swr) * 4 + wc) * 64 + 16 * n + 4 * fq;
;                         hm2 = *(const LAS f32x4*)hp; hm1 = *(const LAS f32x4*)(hp + 32); }
;                 } else { hm2 = *(const f32x4*)(state + (size_t)(sb * 2) * DFF + f); hm1 = *(const f32x4*)(state + (size_t)(sb * 2 + 1) * DFF + f); }
;                 f32x4 p1 = hm1, p2;
; #pragma unroll
;                 for (int j = 0; j < 4; ++j) p2[j] = fr == 1 ? hm1[j] : hm2[j];
; #pragma unroll
;                 for (int m = 0; m < 4; ++m) {
;                     const f32x4 g = acc[ai][0][m][n] * rs[ai][m];
;                     f32x4 gm1, gm2;
; #pragma unroll
;                     for (int j = 0; j < 4; ++j) {
;                         gm1[j] = __int_as_float(__builtin_amdgcn_update_dpp(__float_as_int(p1[j]), __float_as_int(g[j]), 0x111, 0xf, 0xf, false));
;                         gm2[j] = __int_as_float(__builtin_amdgcn_update_dpp(__float_as_int(p2[j]), __float_as_int(g[j]), 0x112, 0xf, 0xf, false));
;                         if (m < 3) {
;                             p1[j] = __int_as_float(__builtin_amdgcn_update_dpp(0, __float_as_int(g[j]), 0x121, 0xf, 0xf, false));
;                             p2[j] = __int_as_float(__builtin_amdgcn_update_dpp(0, __float_as_int(g[j]), 0x122, 0xf, 0xf, false)); }
;                     }
;                     const f32x4 cv = cb[n] + w0[n] * gm2 + w1[n] * gm1 + w2[n] * g;
;                     const f32x4 up = acc[ai][1][m][n] * rs[ai][m];
;                     f32x4 y;
; #pragma unroll
;                     for (int j = 0; j < 4; ++j) y[j] = cv[j] * __builtin_amdgcn_rcpf(1.f + __builtin_amdgcn_exp2f(-cv[j] * LOG2E)) * up[j];
;                     const int tok = tok0 + 128 * ai + 16 * m;
;                     bool ok = true;
;                     if (prompt && ai == 0 && m == 0) ok = (64 * wr + fr) >= 2;
;                     if (lastT) ok = ok && tok < SEQ;
;                     if (ok) *(u32x2*)(Y + ((unsigned)tok * (unsigned)DFF + (unsigned)f)) = pk4(y);
	v_fmac_f32_dpp v220, v250, v162 row_ror:12 row_mask:0xf bank_mask:0xf
	v_cvt_pk_bf16_f32 v113, v114, v115
	v_fmac_f32_dpp v221, v251, v163 row_ror:12 row_mask:0xf bank_mask:0xf
	v_fmac_f32_dpp v218, v248, v164 row_ror:10 row_mask:0xf bank_mask:0xf
	v_fmac_f32_dpp v219, v249, v165 row_ror:10 row_mask:0xf bank_mask:0xf
	v_fmac_f32_dpp v220, v250, v166 row_ror:10 row_mask:0xf bank_mask:0xf
	v_fmac_f32_dpp v221, v251, v167 row_ror:10 row_mask:0xf bank_mask:0xf
	s_and_saveexec_b64 s[28:29], s[66:67]
	global_store_dwordx2 v213, v[112:113], s[46:47] sc1
	s_mov_b64 exec, s[28:29]
	s_add_u32 s46, s46, 0x6e000
	s_addc_u32 s47, s47, 0
	v_pk_mul_f32 v[204:205], v[218:219], v[184:185] op_sel:[0,1] op_sel_hi:[1,1]
	v_pk_mul_f32 v[100:101], v[100:101], v[192:193] op_sel_hi:[1,0]
	v_pk_mul_f32 v[206:207], v[220:221], v[184:185] op_sel:[0,1] op_sel_hi:[1,1]
	v_pk_mul_f32 v[102:103], v[102:103], v[192:193] op_sel_hi:[1,0]
	v_exp_f32_e32 v204, v204
	v_pk_mul_f32 v[96:97], v[96:97], v[192:193] op_sel_hi:[1,0]
	v_exp_f32_e32 v205, v205
	v_pk_mul_f32 v[98:99], v[98:99], v[192:193] op_sel_hi:[1,0]
	v_exp_f32_e32 v206, v206
	v_pk_fma_f32 v[222:223], v[128:129], v[100:101], v[136:137]
	v_exp_f32_e32 v207, v207
	v_pk_fma_f32 v[224:225], v[130:131], v[102:103], v[138:139]
	v_pk_add_f32 v[204:205], v[204:205], 1.0 op_sel_hi:[1,0]
	v_fmac_f32_dpp v222, v100, v124 row_ror:1 row_mask:0xf bank_mask:0xf
	v_pk_add_f32 v[206:207], v[206:207], 1.0 op_sel_hi:[1,0]
	v_fmac_f32_dpp v223, v101, v125 row_ror:1 row_mask:0xf bank_mask:0xf
	v_rcp_f32_e32 v204, v204
	v_fmac_f32_dpp v224, v102, v126 row_ror:1 row_mask:0xf bank_mask:0xf
	v_rcp_f32_e32 v205, v205
	v_fmac_f32_dpp v225, v103, v127 row_ror:1 row_mask:0xf bank_mask:0xf
	v_rcp_f32_e32 v206, v206
	v_fmac_f32_dpp v222, v100, v132 row_ror:2 row_mask:0xf bank_mask:0xf
	v_rcp_f32_e32 v207, v207
	v_fmac_f32_dpp v223, v101, v133 row_ror:2 row_mask:0xf bank_mask:0xf
	v_pk_mul_f32 v[218:219], v[218:219], v[204:205]
	v_fmac_f32_dpp v224, v102, v134 row_ror:2 row_mask:0xf bank_mask:0xf
	v_pk_mul_f32 v[220:221], v[220:221], v[206:207]
	v_fmac_f32_dpp v225, v103, v135 row_ror:2 row_mask:0xf bank_mask:0xf
	v_pk_mul_f32 v[104:105], v[104:105], v[218:219]
	v_fmac_f32_dpp v222, v108, v160 row_ror:1 row_mask:0xf bank_mask:0xf
	v_pk_mul_f32 v[106:107], v[106:107], v[220:221]
	v_fmac_f32_dpp v223, v109, v161 row_ror:1 row_mask:0xf bank_mask:0xf
	v_cvt_pk_bf16_f32 v104, v104, v105
	v_fmac_f32_dpp v224, v110, v162 row_ror:1 row_mask:0xf bank_mask:0xf
	v_cvt_pk_bf16_f32 v105, v106, v107
	v_fmac_f32_dpp v225, v111, v163 row_ror:1 row_mask:0xf bank_mask:0xf
	v_fmac_f32_dpp v222, v108, v164 row_ror:2 row_mask:0xf bank_mask:0xf
	v_fmac_f32_dpp v223, v109, v165 row_ror:2 row_mask:0xf bank_mask:0xf
	v_fmac_f32_dpp v224, v110, v166 row_ror:2 row_mask:0xf bank_mask:0xf
	v_fmac_f32_dpp v225, v111, v167 row_ror:2 row_mask:0xf bank_mask:0xf
	s_and_saveexec_b64 s[28:29], s[68:69]
	global_store_dwordx2 v213, v[104:105], s[46:47] sc1
	s_mov_b64 exec, s[28:29]
	s_add_u32 s46, s46, 0x16000
	s_addc_u32 s47, s47, 0
	v_pk_mul_f32 v[204:205], v[222:223], v[184:185] op_sel:[0,1] op_sel_hi:[1,1]
	v_pk_mul_f32 v[92:93], v[92:93], v[190:191] op_sel_hi:[1,0]
	v_pk_mul_f32 v[206:207], v[224:225], v[184:185] op_sel:[0,1] op_sel_hi:[1,1]
	v_pk_mul_f32 v[94:95], v[94:95], v[190:191] op_sel_hi:[1,0]
	v_exp_f32_e32 v204, v204
	v_pk_mul_f32 v[88:89], v[88:89], v[190:191] op_sel_hi:[1,0]
	v_exp_f32_e32 v205, v205
	v_pk_mul_f32 v[90:91], v[90:91], v[190:191] op_sel_hi:[1,0]
	v_exp_f32_e32 v206, v206
	v_pk_fma_f32 v[218:219], v[128:129], v[92:93], v[136:137]
	v_exp_f32_e32 v207, v207
	v_pk_fma_f32 v[220:221], v[130:131], v[94:95], v[138:139]
	v_pk_add_f32 v[204:205], v[204:205], 1.0 op_sel_hi:[1,0]
	v_fmac_f32_dpp v218, v92, v124 row_ror:1 row_mask:0xf bank_mask:0xf
	v_pk_add_f32 v[206:207], v[206:207], 1.0 op_sel_hi:[1,0]
	v_fmac_f32_dpp v219, v93, v125 row_ror:1 row_mask:0xf bank_mask:0xf
	v_rcp_f32_e32 v204, v204
	v_fmac_f32_dpp v220, v94, v126 row_ror:1 row_mask:0xf bank_mask:0xf
	v_rcp_f32_e32 v205, v205
	v_fmac_f32_dpp v221, v95, v127 row_ror:1 row_mask:0xf bank_mask:0xf
	v_rcp_f32_e32 v206, v206
	v_fmac_f32_dpp v218, v92, v132 row_ror:2 row_mask:0xf bank_mask:0xf
	v_rcp_f32_e32 v207, v207
	v_fmac_f32_dpp v219, v93, v133 row_ror:2 row_mask:0xf bank_mask:0xf
	v_pk_mul_f32 v[222:223], v[222:223], v[204:205]
	v_fmac_f32_dpp v220, v94, v134 row_ror:2 row_mask:0xf bank_mask:0xf
	v_pk_mul_f32 v[224:225], v[224:225], v[206:207]
	v_fmac_f32_dpp v221, v95, v135 row_ror:2 row_mask:0xf bank_mask:0xf
	v_pk_mul_f32 v[96:97], v[96:97], v[222:223]
	v_fmac_f32_dpp v218, v100, v160 row_ror:1 row_mask:0xf bank_mask:0xf
	v_pk_mul_f32 v[98:99], v[98:99], v[224:225]
	v_fmac_f32_dpp v219, v101, v161 row_ror:1 row_mask:0xf bank_mask:0xf
	v_cvt_pk_bf16_f32 v96, v96, v97
	v_fmac_f32_dpp v220, v102, v162 row_ror:1 row_mask:0xf bank_mask:0xf
	v_cvt_pk_bf16_f32 v97, v98, v99
	v_fmac_f32_dpp v221, v103, v163 row_ror:1 row_mask:0xf bank_mask:0xf
	v_fmac_f32_dpp v218, v100, v164 row_ror:2 row_mask:0xf bank_mask:0xf
	v_fmac_f32_dpp v219, v101, v165 row_ror:2 row_mask:0xf bank_mask:0xf
	v_fmac_f32_dpp v220, v102, v166 row_ror:2 row_mask:0xf bank_mask:0xf
	v_fmac_f32_dpp v221, v103, v167 row_ror:2 row_mask:0xf bank_mask:0xf
	s_and_saveexec_b64 s[28:29], s[70:71]
	global_store_dwordx2 v213, v[96:97], s[46:47] sc1
	s_mov_b64 exec, s[28:29]
	s_add_u32 s46, s46, 0x16000
	s_addc_u32 s47, s47, 0
	v_pk_mul_f32 v[204:205], v[218:219], v[184:185] op_sel:[0,1] op_sel_hi:[1,1]
	v_pk_mul_f32 v[84:85], v[84:85], v[184:185] op_sel_hi:[1,0]
	v_pk_mul_f32 v[206:207], v[220:221], v[184:185] op_sel:[0,1] op_sel_hi:[1,1]
; #define LAS __attribute__((address_space(3)))
;     DI void operator()(const AccT& acc, const Unit& u, int wr, int wc, int fr, int fq, LAS unsigned char* ldsx) const {
;     ...
;         for (int n = 0; n < 2; ++n) { const int f = u.pn * 128 + wc * 32 + 16 * n + 4 * fq;
;             w0[n] = *(const f32x4*)(convw + f); w1[n] = *(const f32x4*)(convw + DFF + f); w2[n] = *(const f32x4*)(convw + 2 * DFF + f); cb[n] = *(const f32x4*)(convb + f); }
;         float rs[2][4];
; #pragma unroll
;         for (int ai = 0; ai < 2; ++ai)
; #pragma unroll
;             for (int m = 0; m < 4; ++m) { const int tok = tok0 + 128 * ai + 16 * m; const bool ok = tok >= 0 && tok < (prompt ? SEQ : MTOK);
;                 rs[ai][m] = ok ? rsqrtf(sumsq[ok ? tok : 0] * (1.f / DM) + EPS) : 0.f; }
;         if (prompt) {
;             if (fr >= 14) {
; #pragma unroll
;                 for (int ai = 0; ai < 2; ++ai)
; #pragma unroll
;                     for (int n = 0; n < 2; ++n) *(LAS f32x4*)(H + ((ai * 2 + wr) * 4 + wc) * 64 + (fr - 14) * 32 + 16 * n + 4 * fq) = acc[ai][0][3][n] * rs[ai][3];
;             }
;             asm volatile("s_waitcnt lgkmcnt(0)" ::: "memory"); __builtin_amdgcn_s_barrier(); asm volatile("" ::: "memory");
;         }
; #pragma unroll
;         for (int n = 0; n < 2; ++n) {
;             const int f = u.pn * 128 + wc * 32 + 16 * n + 4 * fq;
; #pragma unroll
;             for (int ai = 0; ai < 2; ++ai) {
;                 f32x4 hm1 = {0.f, 0.f, 0.f, 0.f}, hm2 = {0.f, 0.f, 0.f, 0.f};
;                 const int sb = 4 * (T - GU_PT) + 2 * ai + wr;
;                 if (prompt) {
;                     if (ai | wr) { const int sai = wr ? ai : ai - 1, swr = wr ^ 1; const LAS float* hp = H + ((sai * 2 + swr) * 4 + wc) * 64 + 16 * n + 4 * fq;
;                         hm2 = *(const LAS f32x4*)hp; hm1 = *(const LAS f32x4*)(hp + 32); }
;                 } else { hm2 = *(const f32x4*)(state + (size_t)(sb * 2) * DFF + f); hm1 = *(const f32x4*)(state + (size_t)(sb * 2 + 1) * DFF + f); }
;                 f32x4 p1 = hm1, p2;
; #pragma unroll
;                 for (int j = 0; j < 4; ++j) p2[j] = fr == 1 ? hm1[j] : hm2[j];
; #pragma unroll
;                 for (int m = 0; m < 4; ++m) {
;                     const f32x4 g = acc[ai][0][m][n] * rs[ai][m];
;                     f32x4 gm1, gm2;
; #pragma unroll
;                     for (int j = 0; j < 4; ++j) {
	v_pk_mul_f32 v[86:87], v[86:87], v[184:185] op_sel_hi:[1,0]
	v_exp_f32_e32 v204, v204
	v_pk_mul_f32 v[80:81], v[80:81], v[184:185] op_sel_hi:[1,0]
	v_exp_f32_e32 v205, v205
	v_pk_mul_f32 v[82:83], v[82:83], v[184:185] op_sel_hi:[1,0]
	v_exp_f32_e32 v206, v206
	v_pk_fma_f32 v[222:223], v[128:129], v[84:85], v[136:137]
	v_exp_f32_e32 v207, v207
	v_pk_fma_f32 v[224:225], v[130:131], v[86:87], v[138:139]
	v_pk_add_f32 v[204:205], v[204:205], 1.0 op_sel_hi:[1,0]
	v_fmac_f32_dpp v222, v84, v124 row_ror:1 row_mask:0xf bank_mask:0xf
	v_pk_add_f32 v[206:207], v[206:207], 1.0 op_sel_hi:[1,0]
	v_fmac_f32_dpp v223, v85, v125 row_ror:1 row_mask:0xf bank_mask:0xf
	v_rcp_f32_e32 v204, v204
	v_fmac_f32_dpp v224, v86, v126 row_ror:1 row_mask:0xf bank_mask:0xf
	v_rcp_f32_e32 v205, v205
	v_fmac_f32_dpp v225, v87, v127 row_ror:1 row_mask:0xf bank_mask:0xf
	v_rcp_f32_e32 v206, v206
	v_fmac_f32_dpp v222, v84, v132 row_ror:2 row_mask:0xf bank_mask:0xf
	v_rcp_f32_e32 v207, v207
	v_fmac_f32_dpp v223, v85, v133 row_ror:2 row_mask:0xf bank_mask:0xf
	v_pk_mul_f32 v[218:219], v[218:219], v[204:205]
	v_fmac_f32_dpp v224, v86, v134 row_ror:2 row_mask:0xf bank_mask:0xf
	v_pk_mul_f32 v[220:221], v[220:221], v[206:207]
	v_fmac_f32_dpp v225, v87, v135 row_ror:2 row_mask:0xf bank_mask:0xf
	v_pk_mul_f32 v[88:89], v[88:89], v[218:219]
	v_fmac_f32_dpp v222, v92, v160 row_ror:1 row_mask:0xf bank_mask:0xf
	v_pk_mul_f32 v[90:91], v[90:91], v[220:221]
	v_fmac_f32_dpp v223, v93, v161 row_ror:1 row_mask:0xf bank_mask:0xf
	v_cvt_pk_bf16_f32 v88, v88, v89
	v_fmac_f32_dpp v224, v94, v162 row_ror:1 row_mask:0xf bank_mask:0xf
	v_cvt_pk_bf16_f32 v89, v90, v91
	v_fmac_f32_dpp v225, v95, v163 row_ror:1 row_mask:0xf bank_mask:0xf
	v_fmac_f32_dpp v222, v92, v164 row_ror:2 row_mask:0xf bank_mask:0xf
	v_fmac_f32_dpp v223, v93, v165 row_ror:2 row_mask:0xf bank_mask:0xf
	v_fmac_f32_dpp v224, v94, v166 row_ror:2 row_mask:0xf bank_mask:0xf
	v_fmac_f32_dpp v225, v95, v167 row_ror:2 row_mask:0xf bank_mask:0xf
	s_and_saveexec_b64 s[28:29], s[72:73]
	global_store_dwordx2 v213, v[88:89], s[46:47] sc1
	s_mov_b64 exec, s[28:29]
	s_add_u32 s46, s46, 0x16000
	s_addc_u32 s47, s47, 0
	v_cndmask_b32_e64 v160, 0, v48, s[94:95]
	v_cndmask_b32_e64 v48, v48, 0, s[94:95]
	v_cndmask_b32_e64 v164, 0, v44, s[96:97]
	v_cndmask_b32_e64 v44, v44, 0, s[96:97]
	v_cndmask_b32_e64 v161, 0, v49, s[94:95]
	v_cndmask_b32_e64 v49, v49, 0, s[94:95]
	v_cndmask_b32_e64 v165, 0, v45, s[96:97]
	v_cndmask_b32_e64 v45, v45, 0, s[96:97]
	v_cndmask_b32_e64 v162, 0, v50, s[94:95]
	v_cndmask_b32_e64 v50, v50, 0, s[94:95]
	v_cndmask_b32_e64 v166, 0, v46, s[96:97]
	v_cndmask_b32_e64 v46, v46, 0, s[96:97]
	v_cndmask_b32_e64 v163, 0, v51, s[94:95]
	v_cndmask_b32_e64 v51, v51, 0, s[94:95]
	v_cndmask_b32_e64 v167, 0, v47, s[96:97]
	v_cndmask_b32_e64 v47, v47, 0, s[96:97]
	v_pk_mul_f32 v[204:205], v[222:223], v[184:185] op_sel:[0,1] op_sel_hi:[1,1]
	v_pk_mul_f32 v[76:77], v[76:77], v[214:215] op_sel_hi:[1,0]
	v_pk_mul_f32 v[206:207], v[224:225], v[184:185] op_sel:[0,1] op_sel_hi:[1,1]
	v_pk_mul_f32 v[78:79], v[78:79], v[214:215] op_sel_hi:[1,0]
	v_exp_f32_e32 v204, v204
	v_pk_mul_f32 v[72:73], v[72:73], v[214:215] op_sel_hi:[1,0]
	v_exp_f32_e32 v205, v205
	v_pk_mul_f32 v[74:75], v[74:75], v[214:215] op_sel_hi:[1,0]
	v_exp_f32_e32 v206, v206
	v_pk_fma_f32 v[218:219], v[52:53], v[76:77], v[56:57]
	v_exp_f32_e32 v207, v207
	v_pk_fma_f32 v[220:221], v[54:55], v[78:79], v[58:59]
	v_pk_add_f32 v[204:205], v[204:205], 1.0 op_sel_hi:[1,0]
	v_fmac_f32_dpp v218, v76, v48 row_ror:1 row_mask:0xf bank_mask:0xf
	v_pk_add_f32 v[206:207], v[206:207], 1.0 op_sel_hi:[1,0]
	v_fmac_f32_dpp v219, v77, v49 row_ror:1 row_mask:0xf bank_mask:0xf
	v_rcp_f32_e32 v204, v204
	v_fmac_f32_dpp v220, v78, v50 row_ror:1 row_mask:0xf bank_mask:0xf
	v_rcp_f32_e32 v205, v205
	v_fmac_f32_dpp v221, v79, v51 row_ror:1 row_mask:0xf bank_mask:0xf
	v_rcp_f32_e32 v206, v206
	v_fmac_f32_dpp v218, v76, v44 row_ror:2 row_mask:0xf bank_mask:0xf
	v_rcp_f32_e32 v207, v207
	v_fmac_f32_dpp v219, v77, v45 row_ror:2 row_mask:0xf bank_mask:0xf
	v_pk_mul_f32 v[222:223], v[222:223], v[204:205]
	v_fmac_f32_dpp v220, v78, v46 row_ror:2 row_mask:0xf bank_mask:0xf
	v_pk_mul_f32 v[224:225], v[224:225], v[206:207]
	v_fmac_f32_dpp v221, v79, v47 row_ror:2 row_mask:0xf bank_mask:0xf
	v_pk_mul_f32 v[80:81], v[80:81], v[222:223]
	v_fmac_f32_dpp v218, v248, v160 row_ror:8 row_mask:0xf bank_mask:0xf
	v_pk_mul_f32 v[82:83], v[82:83], v[224:225]
	v_fmac_f32_dpp v219, v249, v161 row_ror:8 row_mask:0xf bank_mask:0xf
	v_cvt_pk_bf16_f32 v80, v80, v81
	v_fmac_f32_dpp v220, v250, v162 row_ror:8 row_mask:0xf bank_mask:0xf
	v_cvt_pk_bf16_f32 v81, v82, v83
	v_fmac_f32_dpp v221, v251, v163 row_ror:8 row_mask:0xf bank_mask:0xf
	v_fmac_f32_dpp v218, v248, v164 row_ror:6 row_mask:0xf bank_mask:0xf
	v_fmac_f32_dpp v219, v249, v165 row_ror:6 row_mask:0xf bank_mask:0xf
	v_fmac_f32_dpp v220, v250, v166 row_ror:6 row_mask:0xf bank_mask:0xf
	v_fmac_f32_dpp v221, v251, v167 row_ror:6 row_mask:0xf bank_mask:0xf
	s_and_saveexec_b64 s[28:29], s[74:75]
	global_store_dwordx2 v213, v[80:81], s[46:47] sc1
	s_mov_b64 exec, s[28:29]
	s_add_u32 s46, s54, 0xfffea000
	s_addc_u32 s47, s55, -1
	v_pk_mul_f32 v[204:205], v[218:219], v[184:185] op_sel:[0,1] op_sel_hi:[1,1]
	v_pk_mul_f32 v[68:69], v[68:69], v[210:211] op_sel_hi:[1,0]
	v_pk_mul_f32 v[206:207], v[220:221], v[184:185] op_sel:[0,1] op_sel_hi:[1,1]
	v_pk_mul_f32 v[70:71], v[70:71], v[210:211] op_sel_hi:[1,0]
	v_exp_f32_e32 v204, v204
	v_pk_mul_f32 v[64:65], v[64:65], v[210:211] op_sel_hi:[1,0]
	v_exp_f32_e32 v205, v205
	v_pk_mul_f32 v[66:67], v[66:67], v[210:211] op_sel_hi:[1,0]
; DI u32x2 pk4(f32x4 v) { u32x2 r; r.x = pk2(v[0], v[1]); r.y = pk2(v[2], v[3]); return r; }
;     DI void operator()(const AccT& acc, const Unit& u, int wr, int wc, int fr, int fq, LAS unsigned char* ldsx) const {
;     ...
;                 for (int m = 0; m < 4; ++m) {
;                     const f32x4 g = acc[ai][0][m][n] * rs[ai][m];
;                     f32x4 gm1, gm2;
; #pragma unroll
;                     for (int j = 0; j < 4; ++j) {
;                         gm1[j] = __int_as_float(__builtin_amdgcn_update_dpp(__float_as_int(p1[j]), __float_as_int(g[j]), 0x111, 0xf, 0xf, false));
;                         gm2[j] = __int_as_float(__builtin_amdgcn_update_dpp(__float_as_int(p2[j]), __float_as_int(g[j]), 0x112, 0xf, 0xf, false));
;                         if (m < 3) {
;                             p1[j] = __int_as_float(__builtin_amdgcn_update_dpp(0, __float_as_int(g[j]), 0x121, 0xf, 0xf, false));
;                             p2[j] = __int_as_float(__builtin_amdgcn_update_dpp(0, __float_as_int(g[j]), 0x122, 0xf, 0xf, false)); }
;                     }
;                     const f32x4 cv = cb[n] + w0[n] * gm2 + w1[n] * gm1 + w2[n] * g;
;                     const f32x4 up = acc[ai][1][m][n] * rs[ai][m];
;                     f32x4 y;
; #pragma unroll
;                     for (int j = 0; j < 4; ++j) y[j] = cv[j] * __builtin_amdgcn_rcpf(1.f + __builtin_amdgcn_exp2f(-cv[j] * LOG2E)) * up[j];
;                     const int tok = tok0 + 128 * ai + 16 * m;
;                     bool ok = true;
;                     if (prompt && ai == 0 && m == 0) ok = (64 * wr + fr) >= 2;
;                     if (lastT) ok = ok && tok < SEQ;
;                     if (ok) *(u32x2*)(Y + ((unsigned)tok * (unsigned)DFF + (unsigned)f)) = pk4(y);
	v_exp_f32_e32 v206, v206
	v_pk_fma_f32 v[222:223], v[52:53], v[68:69], v[56:57]
	v_exp_f32_e32 v207, v207
	v_pk_fma_f32 v[224:225], v[54:55], v[70:71], v[58:59]
	v_pk_add_f32 v[204:205], v[204:205], 1.0 op_sel_hi:[1,0]
	v_fmac_f32_dpp v222, v68, v48 row_ror:1 row_mask:0xf bank_mask:0xf
	v_pk_add_f32 v[206:207], v[206:207], 1.0 op_sel_hi:[1,0]
	v_fmac_f32_dpp v223, v69, v49 row_ror:1 row_mask:0xf bank_mask:0xf
	v_rcp_f32_e32 v204, v204
	v_fmac_f32_dpp v224, v70, v50 row_ror:1 row_mask:0xf bank_mask:0xf
	v_rcp_f32_e32 v205, v205
	v_fmac_f32_dpp v225, v71, v51 row_ror:1 row_mask:0xf bank_mask:0xf
	v_rcp_f32_e32 v206, v206
	v_fmac_f32_dpp v222, v68, v44 row_ror:2 row_mask:0xf bank_mask:0xf
	v_rcp_f32_e32 v207, v207
	v_fmac_f32_dpp v223, v69, v45 row_ror:2 row_mask:0xf bank_mask:0xf
	v_pk_mul_f32 v[218:219], v[218:219], v[204:205]
	v_fmac_f32_dpp v224, v70, v46 row_ror:2 row_mask:0xf bank_mask:0xf
	v_pk_mul_f32 v[220:221], v[220:221], v[206:207]
	v_fmac_f32_dpp v225, v71, v47 row_ror:2 row_mask:0xf bank_mask:0xf
	v_pk_mul_f32 v[72:73], v[72:73], v[218:219]
	v_fmac_f32_dpp v222, v76, v160 row_ror:1 row_mask:0xf bank_mask:0xf
	v_pk_mul_f32 v[74:75], v[74:75], v[220:221]
	v_fmac_f32_dpp v223, v77, v161 row_ror:1 row_mask:0xf bank_mask:0xf
	v_cvt_pk_bf16_f32 v72, v72, v73
	v_fmac_f32_dpp v224, v78, v162 row_ror:1 row_mask:0xf bank_mask:0xf
	v_cvt_pk_bf16_f32 v73, v74, v75
	v_fmac_f32_dpp v225, v79, v163 row_ror:1 row_mask:0xf bank_mask:0xf
	v_fmac_f32_dpp v222, v76, v164 row_ror:2 row_mask:0xf bank_mask:0xf
	v_fmac_f32_dpp v223, v77, v165 row_ror:2 row_mask:0xf bank_mask:0xf
	v_fmac_f32_dpp v224, v78, v166 row_ror:2 row_mask:0xf bank_mask:0xf
	v_fmac_f32_dpp v225, v79, v167 row_ror:2 row_mask:0xf bank_mask:0xf
	s_and_saveexec_b64 s[28:29], s[60:61]
	global_store_dwordx2 v213, v[72:73], s[46:47] offset:32 sc1
	s_mov_b64 exec, s[28:29]
	s_add_u32 s46, s46, 0x16000
	s_addc_u32 s47, s47, 0
	v_pk_mul_f32 v[204:205], v[222:223], v[184:185] op_sel:[0,1] op_sel_hi:[1,1]
	v_pk_mul_f32 v[60:61], v[60:61], v[208:209] op_sel_hi:[1,0]
	v_pk_mul_f32 v[206:207], v[224:225], v[184:185] op_sel:[0,1] op_sel_hi:[1,1]
	v_pk_mul_f32 v[62:63], v[62:63], v[208:209] op_sel_hi:[1,0]
	v_exp_f32_e32 v204, v204
	v_pk_mul_f32 v[40:41], v[40:41], v[208:209] op_sel_hi:[1,0]
	v_exp_f32_e32 v205, v205
	v_pk_mul_f32 v[42:43], v[42:43], v[208:209] op_sel_hi:[1,0]
	v_exp_f32_e32 v206, v206
	v_pk_fma_f32 v[218:219], v[52:53], v[60:61], v[56:57]
	v_exp_f32_e32 v207, v207
	v_pk_fma_f32 v[220:221], v[54:55], v[62:63], v[58:59]
	v_pk_add_f32 v[204:205], v[204:205], 1.0 op_sel_hi:[1,0]
	v_fmac_f32_dpp v218, v60, v48 row_ror:1 row_mask:0xf bank_mask:0xf
	v_pk_add_f32 v[206:207], v[206:207], 1.0 op_sel_hi:[1,0]
	v_fmac_f32_dpp v219, v61, v49 row_ror:1 row_mask:0xf bank_mask:0xf
	v_rcp_f32_e32 v204, v204
	v_fmac_f32_dpp v220, v62, v50 row_ror:1 row_mask:0xf bank_mask:0xf
	v_rcp_f32_e32 v205, v205
	v_fmac_f32_dpp v221, v63, v51 row_ror:1 row_mask:0xf bank_mask:0xf
	v_rcp_f32_e32 v206, v206
	v_fmac_f32_dpp v218, v60, v44 row_ror:2 row_mask:0xf bank_mask:0xf
	v_rcp_f32_e32 v207, v207
	v_fmac_f32_dpp v219, v61, v45 row_ror:2 row_mask:0xf bank_mask:0xf
	v_pk_mul_f32 v[222:223], v[222:223], v[204:205]
	v_fmac_f32_dpp v220, v62, v46 row_ror:2 row_mask:0xf bank_mask:0xf
	v_pk_mul_f32 v[224:225], v[224:225], v[206:207]
	v_fmac_f32_dpp v221, v63, v47 row_ror:2 row_mask:0xf bank_mask:0xf
	v_pk_mul_f32 v[64:65], v[64:65], v[222:223]
	v_fmac_f32_dpp v218, v68, v160 row_ror:1 row_mask:0xf bank_mask:0xf
	v_pk_mul_f32 v[66:67], v[66:67], v[224:225]
	v_fmac_f32_dpp v219, v69, v161 row_ror:1 row_mask:0xf bank_mask:0xf
	v_cvt_pk_bf16_f32 v64, v64, v65
	v_fmac_f32_dpp v220, v70, v162 row_ror:1 row_mask:0xf bank_mask:0xf
	v_cvt_pk_bf16_f32 v65, v66, v67
	v_fmac_f32_dpp v221, v71, v163 row_ror:1 row_mask:0xf bank_mask:0xf
	v_fmac_f32_dpp v218, v68, v164 row_ror:2 row_mask:0xf bank_mask:0xf
	v_fmac_f32_dpp v219, v69, v165 row_ror:2 row_mask:0xf bank_mask:0xf
	v_fmac_f32_dpp v220, v70, v166 row_ror:2 row_mask:0xf bank_mask:0xf
	v_fmac_f32_dpp v221, v71, v167 row_ror:2 row_mask:0xf bank_mask:0xf
	s_and_saveexec_b64 s[28:29], s[62:63]
	global_store_dwordx2 v213, v[64:65], s[46:47] offset:32 sc1
	s_mov_b64 exec, s[28:29]
	s_add_u32 s46, s46, 0x16000
	s_addc_u32 s47, s47, 0
	v_pk_mul_f32 v[204:205], v[218:219], v[184:185] op_sel:[0,1] op_sel_hi:[1,1]
	v_pk_mul_f32 v[36:37], v[36:37], v[202:203] op_sel_hi:[1,0]
	v_pk_mul_f32 v[206:207], v[220:221], v[184:185] op_sel:[0,1] op_sel_hi:[1,1]
	v_pk_mul_f32 v[38:39], v[38:39], v[202:203] op_sel_hi:[1,0]
	v_exp_f32_e32 v204, v204
	v_pk_mul_f32 v[32:33], v[32:33], v[202:203] op_sel_hi:[1,0]
	v_exp_f32_e32 v205, v205
	v_pk_mul_f32 v[34:35], v[34:35], v[202:203] op_sel_hi:[1,0]
	v_exp_f32_e32 v206, v206
	v_pk_fma_f32 v[222:223], v[52:53], v[36:37], v[56:57]
	v_exp_f32_e32 v207, v207
	v_pk_fma_f32 v[224:225], v[54:55], v[38:39], v[58:59]
	v_pk_add_f32 v[204:205], v[204:205], 1.0 op_sel_hi:[1,0]
	v_fmac_f32_dpp v222, v36, v48 row_ror:1 row_mask:0xf bank_mask:0xf
	v_pk_add_f32 v[206:207], v[206:207], 1.0 op_sel_hi:[1,0]
	v_fmac_f32_dpp v223, v37, v49 row_ror:1 row_mask:0xf bank_mask:0xf
	v_rcp_f32_e32 v204, v204
	v_fmac_f32_dpp v224, v38, v50 row_ror:1 row_mask:0xf bank_mask:0xf
	v_rcp_f32_e32 v205, v205
	v_fmac_f32_dpp v225, v39, v51 row_ror:1 row_mask:0xf bank_mask:0xf
	v_rcp_f32_e32 v206, v206
	v_fmac_f32_dpp v222, v36, v44 row_ror:2 row_mask:0xf bank_mask:0xf
	v_rcp_f32_e32 v207, v207
	v_fmac_f32_dpp v223, v37, v45 row_ror:2 row_mask:0xf bank_mask:0xf
	v_pk_mul_f32 v[218:219], v[218:219], v[204:205]
	v_fmac_f32_dpp v224, v38, v46 row_ror:2 row_mask:0xf bank_mask:0xf
; DI u32x2 pk4(f32x4 v) { u32x2 r; r.x = pk2(v[0], v[1]); r.y = pk2(v[2], v[3]); return r; }
;     DI void operator()(const AccT& acc, const Unit& u, int wr, int wc, int fr, int fq, LAS unsigned char* ldsx) const {
;     ...
;                 for (int m = 0; m < 4; ++m) {
;                     const f32x4 g = acc[ai][0][m][n] * rs[ai][m];
;                     f32x4 gm1, gm2;
; #pragma unroll
;                     for (int j = 0; j < 4; ++j) {
;                         gm1[j] = __int_as_float(__builtin_amdgcn_update_dpp(__float_as_int(p1[j]), __float_as_int(g[j]), 0x111, 0xf, 0xf, false));
;                         gm2[j] = __int_as_float(__builtin_amdgcn_update_dpp(__float_as_int(p2[j]), __float_as_int(g[j]), 0x112, 0xf, 0xf, false));
;                         if (m < 3) {
;                             p1[j] = __int_as_float(__builtin_amdgcn_update_dpp(0, __float_as_int(g[j]), 0x121, 0xf, 0xf, false));
;                             p2[j] = __int_as_float(__builtin_amdgcn_update_dpp(0, __float_as_int(g[j]), 0x122, 0xf, 0xf, false)); }
;                     }
;                     const f32x4 cv = cb[n] + w0[n] * gm2 + w1[n] * gm1 + w2[n] * g;
;                     const f32x4 up = acc[ai][1][m][n] * rs[ai][m];
;                     f32x4 y;
; #pragma unroll
;                     for (int j = 0; j < 4; ++j) y[j] = cv[j] * __builtin_amdgcn_rcpf(1.f + __builtin_amdgcn_exp2f(-cv[j] * LOG2E)) * up[j];
;                     const int tok = tok0 + 128 * ai + 16 * m;
;                     bool ok = true;
;                     if (prompt && ai == 0 && m == 0) ok = (64 * wr + fr) >= 2;
;                     if (lastT) ok = ok && tok < SEQ;
;                     if (ok) *(u32x2*)(Y + ((unsigned)tok * (unsigned)DFF + (unsigned)f)) = pk4(y);
	v_pk_mul_f32 v[220:221], v[220:221], v[206:207]
	v_fmac_f32_dpp v225, v39, v47 row_ror:2 row_mask:0xf bank_mask:0xf
	v_pk_mul_f32 v[40:41], v[40:41], v[218:219]
	v_fmac_f32_dpp v222, v60, v160 row_ror:1 row_mask:0xf bank_mask:0xf
	v_pk_mul_f32 v[42:43], v[42:43], v[220:221]
	v_fmac_f32_dpp v223, v61, v161 row_ror:1 row_mask:0xf bank_mask:0xf
	v_cvt_pk_bf16_f32 v40, v40, v41
	v_fmac_f32_dpp v224, v62, v162 row_ror:1 row_mask:0xf bank_mask:0xf
	v_cvt_pk_bf16_f32 v41, v42, v43
	v_fmac_f32_dpp v225, v63, v163 row_ror:1 row_mask:0xf bank_mask:0xf
	v_fmac_f32_dpp v222, v60, v164 row_ror:2 row_mask:0xf bank_mask:0xf
	v_fmac_f32_dpp v223, v61, v165 row_ror:2 row_mask:0xf bank_mask:0xf
	v_fmac_f32_dpp v224, v62, v166 row_ror:2 row_mask:0xf bank_mask:0xf
	v_fmac_f32_dpp v225, v63, v167 row_ror:2 row_mask:0xf bank_mask:0xf
	s_and_saveexec_b64 s[28:29], s[64:65]
	global_store_dwordx2 v213, v[40:41], s[46:47] offset:32 sc1
	s_mov_b64 exec, s[28:29]
	s_add_u32 s46, s46, 0x16000
	s_addc_u32 s47, s47, 0
	v_pk_mul_f32 v[204:205], v[222:223], v[184:185] op_sel:[0,1] op_sel_hi:[1,1]
	v_pk_mul_f32 v[28:29], v[28:29], v[200:201] op_sel_hi:[1,0]
	v_pk_mul_f32 v[206:207], v[224:225], v[184:185] op_sel:[0,1] op_sel_hi:[1,1]
	v_pk_mul_f32 v[30:31], v[30:31], v[200:201] op_sel_hi:[1,0]
	v_exp_f32_e32 v204, v204
	v_pk_mul_f32 v[24:25], v[24:25], v[200:201] op_sel_hi:[1,0]
	v_exp_f32_e32 v205, v205
	v_pk_mul_f32 v[26:27], v[26:27], v[200:201] op_sel_hi:[1,0]
	v_exp_f32_e32 v206, v206
	v_pk_fma_f32 v[218:219], v[52:53], v[28:29], v[56:57]
	v_exp_f32_e32 v207, v207
	v_pk_fma_f32 v[220:221], v[54:55], v[30:31], v[58:59]
	v_pk_add_f32 v[204:205], v[204:205], 1.0 op_sel_hi:[1,0]
	v_fmac_f32_dpp v218, v28, v48 row_ror:1 row_mask:0xf bank_mask:0xf
	v_pk_add_f32 v[206:207], v[206:207], 1.0 op_sel_hi:[1,0]
	v_fmac_f32_dpp v219, v29, v49 row_ror:1 row_mask:0xf bank_mask:0xf
	v_rcp_f32_e32 v204, v204
	v_fmac_f32_dpp v220, v30, v50 row_ror:1 row_mask:0xf bank_mask:0xf
	v_rcp_f32_e32 v205, v205
	v_fmac_f32_dpp v221, v31, v51 row_ror:1 row_mask:0xf bank_mask:0xf
	v_rcp_f32_e32 v206, v206
	v_fmac_f32_dpp v218, v28, v44 row_ror:2 row_mask:0xf bank_mask:0xf
	v_rcp_f32_e32 v207, v207
	v_fmac_f32_dpp v219, v29, v45 row_ror:2 row_mask:0xf bank_mask:0xf
	v_pk_mul_f32 v[222:223], v[222:223], v[204:205]
	v_fmac_f32_dpp v220, v30, v46 row_ror:2 row_mask:0xf bank_mask:0xf
	v_pk_mul_f32 v[224:225], v[224:225], v[206:207]
	v_fmac_f32_dpp v221, v31, v47 row_ror:2 row_mask:0xf bank_mask:0xf
	v_pk_mul_f32 v[32:33], v[32:33], v[222:223]
	v_fmac_f32_dpp v218, v248, v160 row_ror:4 row_mask:0xf bank_mask:0xf
	v_pk_mul_f32 v[34:35], v[34:35], v[224:225]
	v_fmac_f32_dpp v219, v249, v161 row_ror:4 row_mask:0xf bank_mask:0xf
	v_cvt_pk_bf16_f32 v32, v32, v33
	v_fmac_f32_dpp v220, v250, v162 row_ror:4 row_mask:0xf bank_mask:0xf
	v_cvt_pk_bf16_f32 v33, v34, v35
	v_fmac_f32_dpp v221, v251, v163 row_ror:4 row_mask:0xf bank_mask:0xf
	v_fmac_f32_dpp v218, v248, v164 row_ror:2 row_mask:0xf bank_mask:0xf
	v_fmac_f32_dpp v219, v249, v165 row_ror:2 row_mask:0xf bank_mask:0xf
	v_fmac_f32_dpp v220, v250, v166 row_ror:2 row_mask:0xf bank_mask:0xf
	v_fmac_f32_dpp v221, v251, v167 row_ror:2 row_mask:0xf bank_mask:0xf
	s_and_saveexec_b64 s[28:29], s[66:67]
	global_store_dwordx2 v213, v[32:33], s[46:47] offset:32 sc1
	s_mov_b64 exec, s[28:29]
	s_add_u32 s46, s46, 0x6e000
	s_addc_u32 s47, s47, 0
	v_pk_mul_f32 v[204:205], v[218:219], v[184:185] op_sel:[0,1] op_sel_hi:[1,1]
	v_pk_mul_f32 v[20:21], v[20:21], v[192:193] op_sel_hi:[1,0]
	v_pk_mul_f32 v[206:207], v[220:221], v[184:185] op_sel:[0,1] op_sel_hi:[1,1]
	v_pk_mul_f32 v[22:23], v[22:23], v[192:193] op_sel_hi:[1,0]
	v_exp_f32_e32 v204, v204
	v_pk_mul_f32 v[16:17], v[16:17], v[192:193] op_sel_hi:[1,0]
	v_exp_f32_e32 v205, v205
	v_pk_mul_f32 v[18:19], v[18:19], v[192:193] op_sel_hi:[1,0]
	v_exp_f32_e32 v206, v206
	v_pk_fma_f32 v[222:223], v[52:53], v[20:21], v[56:57]
	v_exp_f32_e32 v207, v207
	v_pk_fma_f32 v[224:225], v[54:55], v[22:23], v[58:59]
	v_pk_add_f32 v[204:205], v[204:205], 1.0 op_sel_hi:[1,0]
	v_fmac_f32_dpp v222, v20, v48 row_ror:1 row_mask:0xf bank_mask:0xf
	v_pk_add_f32 v[206:207], v[206:207], 1.0 op_sel_hi:[1,0]
	v_fmac_f32_dpp v223, v21, v49 row_ror:1 row_mask:0xf bank_mask:0xf
	v_rcp_f32_e32 v204, v204
	v_fmac_f32_dpp v224, v22, v50 row_ror:1 row_mask:0xf bank_mask:0xf
	v_rcp_f32_e32 v205, v205
	v_fmac_f32_dpp v225, v23, v51 row_ror:1 row_mask:0xf bank_mask:0xf
	v_rcp_f32_e32 v206, v206
	v_fmac_f32_dpp v222, v20, v44 row_ror:2 row_mask:0xf bank_mask:0xf
	v_rcp_f32_e32 v207, v207
	v_fmac_f32_dpp v223, v21, v45 row_ror:2 row_mask:0xf bank_mask:0xf
	v_pk_mul_f32 v[218:219], v[218:219], v[204:205]
	v_fmac_f32_dpp v224, v22, v46 row_ror:2 row_mask:0xf bank_mask:0xf
	v_pk_mul_f32 v[220:221], v[220:221], v[206:207]
	v_fmac_f32_dpp v225, v23, v47 row_ror:2 row_mask:0xf bank_mask:0xf
	v_pk_mul_f32 v[24:25], v[24:25], v[218:219]
	v_fmac_f32_dpp v222, v28, v160 row_ror:1 row_mask:0xf bank_mask:0xf
	v_pk_mul_f32 v[26:27], v[26:27], v[220:221]
	v_fmac_f32_dpp v223, v29, v161 row_ror:1 row_mask:0xf bank_mask:0xf
	v_cvt_pk_bf16_f32 v24, v24, v25
	v_fmac_f32_dpp v224, v30, v162 row_ror:1 row_mask:0xf bank_mask:0xf
	v_cvt_pk_bf16_f32 v25, v26, v27
	v_fmac_f32_dpp v225, v31, v163 row_ror:1 row_mask:0xf bank_mask:0xf
	v_fmac_f32_dpp v222, v28, v164 row_ror:2 row_mask:0xf bank_mask:0xf
	v_fmac_f32_dpp v223, v29, v165 row_ror:2 row_mask:0xf bank_mask:0xf
	v_fmac_f32_dpp v224, v30, v166 row_ror:2 row_mask:0xf bank_mask:0xf
	v_fmac_f32_dpp v225, v31, v167 row_ror:2 row_mask:0xf bank_mask:0xf
	s_and_saveexec_b64 s[28:29], s[68:69]
	global_store_dwordx2 v213, v[24:25], s[46:47] offset:32 sc1
; DI u32x2 pk4(f32x4 v) { u32x2 r; r.x = pk2(v[0], v[1]); r.y = pk2(v[2], v[3]); return r; }
;     DI void operator()(const AccT& acc, const Unit& u, int wr, int wc, int fr, int fq, LAS unsigned char* ldsx) const {
;     ...
;                 for (int m = 0; m < 4; ++m) {
;                     const f32x4 g = acc[ai][0][m][n] * rs[ai][m];
;                     f32x4 gm1, gm2;
; #pragma unroll
;                     for (int j = 0; j < 4; ++j) {
;                         gm1[j] = __int_as_float(__builtin_amdgcn_update_dpp(__float_as_int(p1[j]), __float_as_int(g[j]), 0x111, 0xf, 0xf, false));
;                         gm2[j] = __int_as_float(__builtin_amdgcn_update_dpp(__float_as_int(p2[j]), __float_as_int(g[j]), 0x112, 0xf, 0xf, false));
;                         if (m < 3) {
;                             p1[j] = __int_as_float(__builtin_amdgcn_update_dpp(0, __float_as_int(g[j]), 0x121, 0xf, 0xf, false));
;                             p2[j] = __int_as_float(__builtin_amdgcn_update_dpp(0, __float_as_int(g[j]), 0x122, 0xf, 0xf, false)); }
;                     }
;                     const f32x4 cv = cb[n] + w0[n] * gm2 + w1[n] * gm1 + w2[n] * g;
;                     const f32x4 up = acc[ai][1][m][n] * rs[ai][m];
;                     f32x4 y;
; #pragma unroll
;                     for (int j = 0; j < 4; ++j) y[j] = cv[j] * __builtin_amdgcn_rcpf(1.f + __builtin_amdgcn_exp2f(-cv[j] * LOG2E)) * up[j];
;                     const int tok = tok0 + 128 * ai + 16 * m;
;                     bool ok = true;
;                     if (prompt && ai == 0 && m == 0) ok = (64 * wr + fr) >= 2;
;                     if (lastT) ok = ok && tok < SEQ;
;                     if (ok) *(u32x2*)(Y + ((unsigned)tok * (unsigned)DFF + (unsigned)f)) = pk4(y);
;                     if (lastT) { if (tok == SEQ - 2 || tok == SEQ - 1) *(f32x4*)(out + OFF_CVP + (size_t)(tok - (SEQ - 2)) * DFF + f) = g; }
;                     if (!prompt && m == 3 && fr >= 14) *(f32x4*)(out + OFF_CVS + (size_t)(sb * 2 + (fr - 14)) * DFF + f) = g;
	s_mov_b64 exec, s[28:29]
	s_add_u32 s46, s46, 0x16000
	s_addc_u32 s47, s47, 0
	v_pk_mul_f32 v[204:205], v[222:223], v[184:185] op_sel:[0,1] op_sel_hi:[1,1]
	v_pk_mul_f32 v[12:13], v[12:13], v[190:191] op_sel_hi:[1,0]
	v_pk_mul_f32 v[206:207], v[224:225], v[184:185] op_sel:[0,1] op_sel_hi:[1,1]
	v_pk_mul_f32 v[14:15], v[14:15], v[190:191] op_sel_hi:[1,0]
	v_exp_f32_e32 v204, v204
	v_pk_mul_f32 v[8:9], v[8:9], v[190:191] op_sel_hi:[1,0]
	v_exp_f32_e32 v205, v205
	v_pk_mul_f32 v[10:11], v[10:11], v[190:191] op_sel_hi:[1,0]
	v_exp_f32_e32 v206, v206
	v_pk_fma_f32 v[218:219], v[52:53], v[12:13], v[56:57]
	v_exp_f32_e32 v207, v207
	v_pk_fma_f32 v[220:221], v[54:55], v[14:15], v[58:59]
	v_pk_add_f32 v[204:205], v[204:205], 1.0 op_sel_hi:[1,0]
	v_fmac_f32_dpp v218, v12, v48 row_ror:1 row_mask:0xf bank_mask:0xf
	v_pk_add_f32 v[206:207], v[206:207], 1.0 op_sel_hi:[1,0]
	v_fmac_f32_dpp v219, v13, v49 row_ror:1 row_mask:0xf bank_mask:0xf
	v_rcp_f32_e32 v204, v204
	v_fmac_f32_dpp v220, v14, v50 row_ror:1 row_mask:0xf bank_mask:0xf
	v_rcp_f32_e32 v205, v205
	v_fmac_f32_dpp v221, v15, v51 row_ror:1 row_mask:0xf bank_mask:0xf
	v_rcp_f32_e32 v206, v206
	v_fmac_f32_dpp v218, v12, v44 row_ror:2 row_mask:0xf bank_mask:0xf
	v_rcp_f32_e32 v207, v207
	v_fmac_f32_dpp v219, v13, v45 row_ror:2 row_mask:0xf bank_mask:0xf
	v_pk_mul_f32 v[222:223], v[222:223], v[204:205]
	v_fmac_f32_dpp v220, v14, v46 row_ror:2 row_mask:0xf bank_mask:0xf
	v_pk_mul_f32 v[224:225], v[224:225], v[206:207]
	v_fmac_f32_dpp v221, v15, v47 row_ror:2 row_mask:0xf bank_mask:0xf
	v_pk_mul_f32 v[16:17], v[16:17], v[222:223]
	v_fmac_f32_dpp v218, v20, v160 row_ror:1 row_mask:0xf bank_mask:0xf
	v_pk_mul_f32 v[18:19], v[18:19], v[224:225]
	v_fmac_f32_dpp v219, v21, v161 row_ror:1 row_mask:0xf bank_mask:0xf
	v_cvt_pk_bf16_f32 v16, v16, v17
	v_fmac_f32_dpp v220, v22, v162 row_ror:1 row_mask:0xf bank_mask:0xf
	v_cvt_pk_bf16_f32 v17, v18, v19
	v_fmac_f32_dpp v221, v23, v163 row_ror:1 row_mask:0xf bank_mask:0xf
	v_fmac_f32_dpp v218, v20, v164 row_ror:2 row_mask:0xf bank_mask:0xf
	v_fmac_f32_dpp v219, v21, v165 row_ror:2 row_mask:0xf bank_mask:0xf
	v_fmac_f32_dpp v220, v22, v166 row_ror:2 row_mask:0xf bank_mask:0xf
	v_fmac_f32_dpp v221, v23, v167 row_ror:2 row_mask:0xf bank_mask:0xf
	s_and_saveexec_b64 s[28:29], s[70:71]
	global_store_dwordx2 v213, v[16:17], s[46:47] offset:32 sc1
	s_mov_b64 exec, s[28:29]
	s_add_u32 s46, s46, 0x16000
	s_addc_u32 s47, s47, 0
	v_pk_mul_f32 v[204:205], v[218:219], v[184:185] op_sel:[0,1] op_sel_hi:[1,1]
	v_pk_mul_f32 v[4:5], v[4:5], v[184:185] op_sel_hi:[1,0]
	v_pk_mul_f32 v[206:207], v[220:221], v[184:185] op_sel:[0,1] op_sel_hi:[1,1]
	v_pk_mul_f32 v[6:7], v[6:7], v[184:185] op_sel_hi:[1,0]
	v_exp_f32_e32 v204, v204
	v_pk_mul_f32 v[0:1], v[0:1], v[184:185] op_sel_hi:[1,0]
	v_exp_f32_e32 v205, v205
	v_pk_mul_f32 v[2:3], v[2:3], v[184:185] op_sel_hi:[1,0]
	v_exp_f32_e32 v206, v206
	v_pk_fma_f32 v[222:223], v[52:53], v[4:5], v[56:57]
	v_exp_f32_e32 v207, v207
	v_pk_fma_f32 v[224:225], v[54:55], v[6:7], v[58:59]
	v_pk_add_f32 v[204:205], v[204:205], 1.0 op_sel_hi:[1,0]
	v_fmac_f32_dpp v222, v4, v48 row_ror:1 row_mask:0xf bank_mask:0xf
	v_pk_add_f32 v[206:207], v[206:207], 1.0 op_sel_hi:[1,0]
	v_fmac_f32_dpp v223, v5, v49 row_ror:1 row_mask:0xf bank_mask:0xf
	v_rcp_f32_e32 v204, v204
	v_fmac_f32_dpp v224, v6, v50 row_ror:1 row_mask:0xf bank_mask:0xf
	v_rcp_f32_e32 v205, v205
	v_fmac_f32_dpp v225, v7, v51 row_ror:1 row_mask:0xf bank_mask:0xf
	v_rcp_f32_e32 v206, v206
	v_fmac_f32_dpp v222, v4, v44 row_ror:2 row_mask:0xf bank_mask:0xf
	v_rcp_f32_e32 v207, v207
	v_fmac_f32_dpp v223, v5, v45 row_ror:2 row_mask:0xf bank_mask:0xf
	v_pk_mul_f32 v[218:219], v[218:219], v[204:205]
	v_fmac_f32_dpp v224, v6, v46 row_ror:2 row_mask:0xf bank_mask:0xf
	v_pk_mul_f32 v[220:221], v[220:221], v[206:207]
	v_fmac_f32_dpp v225, v7, v47 row_ror:2 row_mask:0xf bank_mask:0xf
	v_pk_mul_f32 v[8:9], v[8:9], v[218:219]
	v_fmac_f32_dpp v222, v12, v160 row_ror:1 row_mask:0xf bank_mask:0xf
	v_pk_mul_f32 v[10:11], v[10:11], v[220:221]
	v_fmac_f32_dpp v223, v13, v161 row_ror:1 row_mask:0xf bank_mask:0xf
	v_cvt_pk_bf16_f32 v8, v8, v9
	v_fmac_f32_dpp v224, v14, v162 row_ror:1 row_mask:0xf bank_mask:0xf
	v_cvt_pk_bf16_f32 v9, v10, v11
	v_fmac_f32_dpp v225, v15, v163 row_ror:1 row_mask:0xf bank_mask:0xf
	v_fmac_f32_dpp v222, v12, v164 row_ror:2 row_mask:0xf bank_mask:0xf
	v_fmac_f32_dpp v223, v13, v165 row_ror:2 row_mask:0xf bank_mask:0xf
	v_fmac_f32_dpp v224, v14, v166 row_ror:2 row_mask:0xf bank_mask:0xf
	v_fmac_f32_dpp v225, v15, v167 row_ror:2 row_mask:0xf bank_mask:0xf
	s_and_saveexec_b64 s[28:29], s[72:73]
	global_store_dwordx2 v213, v[8:9], s[46:47] offset:32 sc1
	s_mov_b64 exec, s[28:29]
	s_add_u32 s46, s46, 0x16000
	s_addc_u32 s47, s47, 0
	v_pk_mul_f32 v[204:205], v[222:223], v[184:185] op_sel:[0,1] op_sel_hi:[1,1]
	v_pk_mul_f32 v[206:207], v[224:225], v[184:185] op_sel:[0,1] op_sel_hi:[1,1]
	v_exp_f32_e32 v204, v204
	v_exp_f32_e32 v205, v205
	v_exp_f32_e32 v206, v206
	v_exp_f32_e32 v207, v207
	v_pk_add_f32 v[204:205], v[204:205], 1.0 op_sel_hi:[1,0]
	v_pk_add_f32 v[206:207], v[206:207], 1.0 op_sel_hi:[1,0]
	v_rcp_f32_e32 v204, v204
	v_rcp_f32_e32 v205, v205
	v_rcp_f32_e32 v206, v206
	v_rcp_f32_e32 v207, v207
	v_pk_mul_f32 v[222:223], v[222:223], v[204:205]
	v_pk_mul_f32 v[224:225], v[224:225], v[206:207]
	v_pk_mul_f32 v[0:1], v[0:1], v[222:223]
	v_pk_mul_f32 v[2:3], v[2:3], v[224:225]
	v_cvt_pk_bf16_f32 v0, v0, v1
	v_cvt_pk_bf16_f32 v1, v2, v3
	s_and_saveexec_b64 s[28:29], s[74:75]
	global_store_dwordx2 v213, v[0:1], s[46:47] offset:32 sc1
	s_mov_b64 exec, s[28:29]
	s_add_u32 s46, s54, 0xfffea000
	s_addc_u32 s47, s55, -1
	s_cmp_gt_i32 s42, 64
	s_cbranch_scc0 .Lgu_nocvs
	v_readlane_b32 s30, v252, 0
	v_readlane_b32 s31, v252, 1
	s_lshl_b32 s23, s42, 2
	s_add_i32 s23, s36, s23
	s_lshl_b32 s23, s23, 1
	s_movk_i32 s76, 0x2c00
	v_add_u32_e32 v186, s23, v233
	v_mad_i64_i32 v[186:187], s[34:35], v186, s76, 0
	v_lshl_add_u64 v[186:187], s[14:15], 0, v[186:187]
	v_lshl_add_u64 v[186:187], v[216:217], 2, v[186:187]
	s_and_saveexec_b64 s[28:29], s[30:31]
	global_store_dwordx4 v[186:187], v[116:119], off
	global_store_dwordx4 v[186:187], v[36:39], off offset:64
	s_mov_b64 exec, s[28:29]
	s_add_i32 s23, s23, 4
	v_add_u32_e32 v186, s23, v233
	v_mad_i64_i32 v[186:187], s[34:35], v186, s76, 0
	v_lshl_add_u64 v[186:187], s[14:15], 0, v[186:187]
	v_lshl_add_u64 v[186:187], v[216:217], 2, v[186:187]
	s_and_saveexec_b64 s[28:29], s[30:31]
	global_store_dwordx4 v[186:187], v[84:87], off
	global_store_dwordx4 v[186:187], v[4:7], off offset:64
	s_mov_b64 exec, s[28:29]

; DI u32x2 pk4(f32x4 v) { u32x2 r; r.x = pk2(v[0], v[1]); r.y = pk2(v[2], v[3]); return r; }
;     DI void operator()(const AccT& acc, const Unit& u, int wr, int wc, int fr, int fq, LAS unsigned char*) const {
;     ...
;         for (int ai = 0; ai < 2; ++ai)
; #pragma unroll
;             for (int m = 0; m < 4; ++m) {
;                 const int row = u.pm * 256 + ai * 128 + wr * 64 + m * 16 + fr;
;                 const float* xr = (row < SEQ ? xp + (size_t)row * DM : xs + (size_t)(row - SEQ) * DM) + col0;
;                 bf16_t* brow = X1B + (size_t)(row < SEQ ? row + 2 : row + (X1B_PROMPT_ROWS - SEQ)) * DM + col0;
;                 float ss = 0.f;
; #pragma unroll
;                 for (int bj = 0; bj < 2; ++bj)
; #pragma unroll
;                     for (int n = 0; n < 2; ++n) {
;                         const int c = bj * 128 + n * 16;
;                         const f32x4 o = *(const f32x4*)(xr + c) + acc[ai][bj][m][n];
;                         *(u32x2*)(brow + c) = pk4(o);
;                         ss += (o[0] * o[0] + o[1] * o[1]) + (o[2] * o[2] + o[3] * o[3]);
;                     }
;                 ss += __shfl_xor(ss, 16); ss += __shfl_xor(ss, 32);
;                 if (fq == 0) unsafeAtomicAdd(sumsq + row, ss);
;             }
.LBB0_960:
	v_lshl_add_u32 v130, s31, 8, v132
	v_lshl_or_b32 v128, s33, 8, v134
	s_cmp_lt_i32 s31, 64
	s_cselect_b32 s16, s44, s46
	s_cselect_b32 s17, s45, s47
	s_cselect_b32 s42, 0, 0x4000000
	s_cselect_b32 s43, 1, 64
	s_lshl_b32 s43, s43, 12
	s_sub_u32 s16, s16, s42
	s_subb_u32 s17, s17, 0
	s_add_u32 s18, s56, s43
	s_addc_u32 s19, s57, 0
	v_lshlrev_b32_e32 v129, 12, v130
	v_lshlrev_b32_e32 v131, 11, v130
	v_lshl_add_u32 v129, v128, 2, v129
	v_lshl_add_u32 v131, v128, 1, v131
	v_lshlrev_b32_e32 v130, 2, v130
	global_load_dwordx4 v[146:149], v129, s[16:17]
	global_load_dwordx4 v[150:153], v129, s[16:17] offset:64
	global_load_dwordx4 v[154:157], v129, s[16:17] offset:512
	global_load_dwordx4 v[158:161], v129, s[16:17] offset:576
	s_add_u32 s36, s16, 0x10000
	s_addc_u32 s37, s17, 0
	global_load_dwordx4 v[182:185], v129, s[36:37]
	global_load_dwordx4 v[186:189], v129, s[36:37] offset:64
	global_load_dwordx4 v[190:193], v129, s[36:37] offset:512
	global_load_dwordx4 v[194:197], v129, s[36:37] offset:576
	s_add_u32 s36, s16, 0x20000
	s_addc_u32 s37, s17, 0
	global_load_dwordx4 v[198:201], v129, s[36:37]
	global_load_dwordx4 v[202:205], v129, s[36:37] offset:64
	global_load_dwordx4 v[206:209], v129, s[36:37] offset:512
	global_load_dwordx4 v[210:213], v129, s[36:37] offset:576
	s_add_u32 s36, s16, 0x30000
	s_addc_u32 s37, s17, 0
	global_load_dwordx4 v[162:165], v129, s[36:37]
	global_load_dwordx4 v[214:217], v129, s[36:37] offset:64
	global_load_dwordx4 v[136:139], v129, s[36:37] offset:512
	global_load_dwordx4 v[140:143], v129, s[36:37] offset:576
	s_waitcnt vmcnt(12)
	v_pk_add_f32 v[146:147], v[124:125], v[146:147]
	v_pk_add_f32 v[148:149], v[126:127], v[148:149]
	v_pk_add_f32 v[150:151], v[120:121], v[150:151]
	v_pk_add_f32 v[152:153], v[122:123], v[152:153]
	v_pk_add_f32 v[154:155], v[116:117], v[154:155]
	v_pk_add_f32 v[156:157], v[118:119], v[156:157]
	v_pk_add_f32 v[158:159], v[112:113], v[158:159]
	v_pk_add_f32 v[160:161], v[114:115], v[160:161]
	s_add_u32 s36, s16, 0x80000
	s_addc_u32 s37, s17, 0
	global_load_dwordx4 v[124:127], v129, s[36:37]
	global_load_dwordx4 v[120:123], v129, s[36:37] offset:64
	global_load_dwordx4 v[116:119], v129, s[36:37] offset:512
	global_load_dwordx4 v[112:115], v129, s[36:37] offset:576
	s_waitcnt vmcnt(12)
	v_pk_add_f32 v[182:183], v[108:109], v[182:183]
	v_pk_add_f32 v[184:185], v[110:111], v[184:185]
	v_pk_add_f32 v[186:187], v[104:105], v[186:187]
	v_pk_add_f32 v[188:189], v[106:107], v[188:189]
	v_pk_add_f32 v[190:191], v[100:101], v[190:191]
	v_pk_add_f32 v[192:193], v[102:103], v[192:193]
	v_pk_add_f32 v[194:195], v[96:97], v[194:195]
	v_pk_add_f32 v[196:197], v[98:99], v[196:197]
	s_add_u32 s36, s16, 0x90000
	s_addc_u32 s37, s17, 0
	global_load_dwordx4 v[108:111], v129, s[36:37]
	global_load_dwordx4 v[104:107], v129, s[36:37] offset:64
	global_load_dwordx4 v[100:103], v129, s[36:37] offset:512
	global_load_dwordx4 v[96:99], v129, s[36:37] offset:576
	s_waitcnt vmcnt(12)
	v_pk_add_f32 v[198:199], v[92:93], v[198:199]
	v_pk_add_f32 v[200:201], v[94:95], v[200:201]
	v_pk_add_f32 v[202:203], v[88:89], v[202:203]
	v_pk_add_f32 v[204:205], v[90:91], v[204:205]
	v_pk_add_f32 v[206:207], v[84:85], v[206:207]
	v_pk_add_f32 v[208:209], v[86:87], v[208:209]
	v_pk_add_f32 v[210:211], v[80:81], v[210:211]
	v_pk_add_f32 v[212:213], v[82:83], v[212:213]
	s_add_u32 s36, s16, 0xa0000
	s_addc_u32 s37, s17, 0
	global_load_dwordx4 v[92:95], v129, s[36:37]
	global_load_dwordx4 v[88:91], v129, s[36:37] offset:64
	global_load_dwordx4 v[84:87], v129, s[36:37] offset:512
	global_load_dwordx4 v[80:83], v129, s[36:37] offset:576
	s_waitcnt vmcnt(12)
	v_pk_add_f32 v[162:163], v[76:77], v[162:163]
	v_pk_add_f32 v[164:165], v[78:79], v[164:165]
	v_pk_add_f32 v[214:215], v[72:73], v[214:215]
	v_pk_add_f32 v[216:217], v[74:75], v[216:217]
	v_pk_add_f32 v[136:137], v[68:69], v[136:137]
	v_pk_add_f32 v[138:139], v[70:71], v[138:139]
	v_pk_add_f32 v[140:141], v[64:65], v[140:141]
	v_pk_add_f32 v[142:143], v[66:67], v[142:143]
	s_add_u32 s36, s16, 0xb0000
	s_addc_u32 s37, s17, 0
	global_load_dwordx4 v[76:79], v129, s[36:37]
	global_load_dwordx4 v[72:75], v129, s[36:37] offset:64
	global_load_dwordx4 v[68:71], v129, s[36:37] offset:512
	global_load_dwordx4 v[64:67], v129, s[36:37] offset:576
	v_pk_mul_f32 v[166:167], v[146:147], v[146:147]
	v_pk_mul_f32 v[144:145], v[148:149], v[148:149]
	v_pk_fma_f32 v[166:167], v[150:151], v[150:151], v[166:167]
	v_pk_fma_f32 v[144:145], v[152:153], v[152:153], v[144:145]
	v_pk_fma_f32 v[166:167], v[154:155], v[154:155], v[166:167]
	v_pk_fma_f32 v[144:145], v[156:157], v[156:157], v[144:145]
	v_pk_fma_f32 v[166:167], v[158:159], v[158:159], v[166:167]
	v_pk_fma_f32 v[144:145], v[160:161], v[160:161], v[144:145]
	s_nop 0
	v_pk_add_f32 v[166:167], v[166:167], v[144:145]
	v_cvt_pk_bf16_f32 v146, v146, v147
	v_cvt_pk_bf16_f32 v147, v148, v149
	v_cvt_pk_bf16_f32 v150, v150, v151
	v_cvt_pk_bf16_f32 v151, v152, v153
	v_cvt_pk_bf16_f32 v154, v154, v155
	v_cvt_pk_bf16_f32 v155, v156, v157
	v_cvt_pk_bf16_f32 v158, v158, v159
	v_cvt_pk_bf16_f32 v159, v160, v161
	v_add_f32_e32 v218, v166, v167
	global_store_dwordx2 v131, v[146:147], s[18:19] sc1
	global_store_dwordx2 v131, v[150:151], s[18:19] offset:32 sc1
	global_store_dwordx2 v131, v[154:155], s[18:19] offset:256 sc1
	global_store_dwordx2 v131, v[158:159], s[18:19] offset:288 sc1
	v_mov_b32_e32 v219, v218
	s_nop 1
	v_permlane16_swap_b32_e32 v219, v218
	v_add_f32_e32 v218, v218, v219
	v_mov_b32_e32 v219, v218
	s_nop 1
	v_permlane32_swap_b32_e32 v219, v218
	v_add_f32_e32 v218, v218, v219
	s_and_saveexec_b64 s[0:1], s[40:41]
	global_atomic_add_f32 v130, v218, s[58:59]
; DI u32x2 pk4(f32x4 v) { u32x2 r; r.x = pk2(v[0], v[1]); r.y = pk2(v[2], v[3]); return r; }
;     DI void operator()(const AccT& acc, const Unit& u, int wr, int wc, int fr, int fq, LAS unsigned char*) const {
;     ...
;                 for (int bj = 0; bj < 2; ++bj)
; #pragma unroll
;                     for (int n = 0; n < 2; ++n) {
;                         const int c = bj * 128 + n * 16;
;                         const f32x4 o = *(const f32x4*)(xr + c) + acc[ai][bj][m][n];
;                         *(u32x2*)(brow + c) = pk4(o);
;                         ss += (o[0] * o[0] + o[1] * o[1]) + (o[2] * o[2] + o[3] * o[3]);
;                     }
;                 ss += __shfl_xor(ss, 16); ss += __shfl_xor(ss, 32);
;                 if (fq == 0) unsafeAtomicAdd(sumsq + row, ss);
;             }
	s_mov_b64 exec, s[0:1]
	v_pk_mul_f32 v[166:167], v[182:183], v[182:183]
	v_pk_mul_f32 v[144:145], v[184:185], v[184:185]
	v_pk_fma_f32 v[166:167], v[186:187], v[186:187], v[166:167]
	v_pk_fma_f32 v[144:145], v[188:189], v[188:189], v[144:145]
	v_pk_fma_f32 v[166:167], v[190:191], v[190:191], v[166:167]
	v_pk_fma_f32 v[144:145], v[192:193], v[192:193], v[144:145]
	v_pk_fma_f32 v[166:167], v[194:195], v[194:195], v[166:167]
	v_pk_fma_f32 v[144:145], v[196:197], v[196:197], v[144:145]
	s_nop 0
	v_pk_add_f32 v[166:167], v[166:167], v[144:145]
	s_add_u32 s48, s18, 0x8000
	s_addc_u32 s49, s19, 0
	v_cvt_pk_bf16_f32 v182, v182, v183
	v_cvt_pk_bf16_f32 v183, v184, v185
	v_cvt_pk_bf16_f32 v186, v186, v187
	v_cvt_pk_bf16_f32 v187, v188, v189
	v_cvt_pk_bf16_f32 v190, v190, v191
	v_cvt_pk_bf16_f32 v191, v192, v193
	v_cvt_pk_bf16_f32 v194, v194, v195
	v_cvt_pk_bf16_f32 v195, v196, v197
	v_add_f32_e32 v218, v166, v167
	global_store_dwordx2 v131, v[182:183], s[48:49] sc1
	global_store_dwordx2 v131, v[186:187], s[48:49] offset:32 sc1
	global_store_dwordx2 v131, v[190:191], s[48:49] offset:256 sc1
	global_store_dwordx2 v131, v[194:195], s[48:49] offset:288 sc1
	v_mov_b32_e32 v219, v218
	s_nop 1
	v_permlane16_swap_b32_e32 v219, v218
	v_add_f32_e32 v218, v218, v219
	v_mov_b32_e32 v219, v218
	s_nop 1
	v_permlane32_swap_b32_e32 v219, v218
	v_add_f32_e32 v218, v218, v219
	s_and_saveexec_b64 s[0:1], s[40:41]
	global_atomic_add_f32 v130, v218, s[58:59] offset:64
	s_mov_b64 exec, s[0:1]
	v_pk_mul_f32 v[166:167], v[198:199], v[198:199]
	v_pk_mul_f32 v[144:145], v[200:201], v[200:201]
	v_pk_fma_f32 v[166:167], v[202:203], v[202:203], v[166:167]
	v_pk_fma_f32 v[144:145], v[204:205], v[204:205], v[144:145]
	v_pk_fma_f32 v[166:167], v[206:207], v[206:207], v[166:167]
	v_pk_fma_f32 v[144:145], v[208:209], v[208:209], v[144:145]
	v_pk_fma_f32 v[166:167], v[210:211], v[210:211], v[166:167]
	v_pk_fma_f32 v[144:145], v[212:213], v[212:213], v[144:145]
	s_nop 0
	v_pk_add_f32 v[166:167], v[166:167], v[144:145]
	s_add_u32 s48, s18, 0x10000
	s_addc_u32 s49, s19, 0
	v_cvt_pk_bf16_f32 v198, v198, v199
	v_cvt_pk_bf16_f32 v199, v200, v201
	v_cvt_pk_bf16_f32 v202, v202, v203
	v_cvt_pk_bf16_f32 v203, v204, v205
	v_cvt_pk_bf16_f32 v206, v206, v207
	v_cvt_pk_bf16_f32 v207, v208, v209
	v_cvt_pk_bf16_f32 v210, v210, v211
	v_cvt_pk_bf16_f32 v211, v212, v213
	v_add_f32_e32 v218, v166, v167
	global_store_dwordx2 v131, v[198:199], s[48:49] sc1
	global_store_dwordx2 v131, v[202:203], s[48:49] offset:32 sc1
	global_store_dwordx2 v131, v[206:207], s[48:49] offset:256 sc1
	global_store_dwordx2 v131, v[210:211], s[48:49] offset:288 sc1
	v_mov_b32_e32 v219, v218
	s_nop 1
	v_permlane16_swap_b32_e32 v219, v218
	v_add_f32_e32 v218, v218, v219
	v_mov_b32_e32 v219, v218
	s_nop 1
	v_permlane32_swap_b32_e32 v219, v218
	v_add_f32_e32 v218, v218, v219
	s_and_saveexec_b64 s[0:1], s[40:41]
	global_atomic_add_f32 v130, v218, s[58:59] offset:128
	s_mov_b64 exec, s[0:1]
	v_pk_mul_f32 v[166:167], v[162:163], v[162:163]
	v_pk_mul_f32 v[144:145], v[164:165], v[164:165]
	v_pk_fma_f32 v[166:167], v[214:215], v[214:215], v[166:167]
	v_pk_fma_f32 v[144:145], v[216:217], v[216:217], v[144:145]
	v_pk_fma_f32 v[166:167], v[136:137], v[136:137], v[166:167]
	v_pk_fma_f32 v[144:145], v[138:139], v[138:139], v[144:145]
	v_pk_fma_f32 v[166:167], v[140:141], v[140:141], v[166:167]
	v_pk_fma_f32 v[144:145], v[142:143], v[142:143], v[144:145]
	s_nop 0
	v_pk_add_f32 v[166:167], v[166:167], v[144:145]
	s_add_u32 s48, s18, 0x18000
	s_addc_u32 s49, s19, 0
	v_cvt_pk_bf16_f32 v162, v162, v163
	v_cvt_pk_bf16_f32 v163, v164, v165
	v_cvt_pk_bf16_f32 v214, v214, v215
	v_cvt_pk_bf16_f32 v215, v216, v217
	v_cvt_pk_bf16_f32 v136, v136, v137
	v_cvt_pk_bf16_f32 v137, v138, v139
	v_cvt_pk_bf16_f32 v140, v140, v141
	v_cvt_pk_bf16_f32 v141, v142, v143
	v_add_f32_e32 v218, v166, v167
	global_store_dwordx2 v131, v[162:163], s[48:49] sc1
	global_store_dwordx2 v131, v[214:215], s[48:49] offset:32 sc1
	global_store_dwordx2 v131, v[136:137], s[48:49] offset:256 sc1
	global_store_dwordx2 v131, v[140:141], s[48:49] offset:288 sc1
	v_mov_b32_e32 v219, v218
	s_nop 1
	v_permlane16_swap_b32_e32 v219, v218
	v_add_f32_e32 v218, v218, v219
	v_mov_b32_e32 v219, v218
	s_nop 1
	v_permlane32_swap_b32_e32 v219, v218
	v_add_f32_e32 v218, v218, v219
	s_and_saveexec_b64 s[0:1], s[40:41]
	global_atomic_add_f32 v130, v218, s[58:59] offset:192
	s_mov_b64 exec, s[0:1]
	s_waitcnt vmcnt(32)
	v_pk_add_f32 v[124:125], v[60:61], v[124:125]
	v_pk_add_f32 v[126:127], v[62:63], v[126:127]
	v_pk_add_f32 v[120:121], v[56:57], v[120:121]
	v_pk_add_f32 v[122:123], v[58:59], v[122:123]
	v_pk_add_f32 v[116:117], v[52:53], v[116:117]
	v_pk_add_f32 v[118:119], v[54:55], v[118:119]
	v_pk_add_f32 v[112:113], v[48:49], v[112:113]
	v_pk_add_f32 v[114:115], v[50:51], v[114:115]
	v_pk_mul_f32 v[166:167], v[124:125], v[124:125]
	v_pk_mul_f32 v[144:145], v[126:127], v[126:127]
	v_pk_fma_f32 v[166:167], v[120:121], v[120:121], v[166:167]
	v_pk_fma_f32 v[144:145], v[122:123], v[122:123], v[144:145]
	v_pk_fma_f32 v[166:167], v[116:117], v[116:117], v[166:167]
	v_pk_fma_f32 v[144:145], v[118:119], v[118:119], v[144:145]
	v_pk_fma_f32 v[166:167], v[112:113], v[112:113], v[166:167]
	v_pk_fma_f32 v[144:145], v[114:115], v[114:115], v[144:145]
	s_nop 0
	v_pk_add_f32 v[166:167], v[166:167], v[144:145]
	s_add_u32 s48, s18, 0x40000
	s_addc_u32 s49, s19, 0
	v_cvt_pk_bf16_f32 v124, v124, v125
	v_cvt_pk_bf16_f32 v125, v126, v127
	v_cvt_pk_bf16_f32 v120, v120, v121
	v_cvt_pk_bf16_f32 v121, v122, v123
	v_cvt_pk_bf16_f32 v116, v116, v117
	v_cvt_pk_bf16_f32 v117, v118, v119
	v_cvt_pk_bf16_f32 v112, v112, v113
	v_cvt_pk_bf16_f32 v113, v114, v115
	v_add_f32_e32 v218, v166, v167
	global_store_dwordx2 v131, v[124:125], s[48:49] sc1
	global_store_dwordx2 v131, v[120:121], s[48:49] offset:32 sc1
	global_store_dwordx2 v131, v[116:117], s[48:49] offset:256 sc1
	global_store_dwordx2 v131, v[112:113], s[48:49] offset:288 sc1
	v_mov_b32_e32 v219, v218
	s_nop 1
	v_permlane16_swap_b32_e32 v219, v218
	v_add_f32_e32 v218, v218, v219
	v_mov_b32_e32 v219, v218
	s_nop 1
	v_permlane32_swap_b32_e32 v219, v218
	v_add_f32_e32 v218, v218, v219
	s_and_saveexec_b64 s[0:1], s[40:41]
	global_atomic_add_f32 v130, v218, s[58:59] offset:512
	s_mov_b64 exec, s[0:1]
	s_waitcnt vmcnt(33)
; DI u32x2 pk4(f32x4 v) { u32x2 r; r.x = pk2(v[0], v[1]); r.y = pk2(v[2], v[3]); return r; }
;     DI void operator()(const AccT& acc, const Unit& u, int wr, int wc, int fr, int fq, LAS unsigned char*) const {
;     ...
;                 for (int bj = 0; bj < 2; ++bj)
; #pragma unroll
;                     for (int n = 0; n < 2; ++n) {
;                         const int c = bj * 128 + n * 16;
;                         const f32x4 o = *(const f32x4*)(xr + c) + acc[ai][bj][m][n];
;                         *(u32x2*)(brow + c) = pk4(o);
;                         ss += (o[0] * o[0] + o[1] * o[1]) + (o[2] * o[2] + o[3] * o[3]);
;                     }
;                 ss += __shfl_xor(ss, 16); ss += __shfl_xor(ss, 32);
;                 if (fq == 0) unsafeAtomicAdd(sumsq + row, ss);
;             }
	v_pk_add_f32 v[108:109], v[44:45], v[108:109]
	v_pk_add_f32 v[110:111], v[46:47], v[110:111]
	v_pk_add_f32 v[104:105], v[40:41], v[104:105]
	v_pk_add_f32 v[106:107], v[42:43], v[106:107]
	v_pk_add_f32 v[100:101], v[36:37], v[100:101]
	v_pk_add_f32 v[102:103], v[38:39], v[102:103]
	v_pk_add_f32 v[96:97], v[32:33], v[96:97]
	v_pk_add_f32 v[98:99], v[34:35], v[98:99]
	v_pk_mul_f32 v[166:167], v[108:109], v[108:109]
	v_pk_mul_f32 v[144:145], v[110:111], v[110:111]
	v_pk_fma_f32 v[166:167], v[104:105], v[104:105], v[166:167]
	v_pk_fma_f32 v[144:145], v[106:107], v[106:107], v[144:145]
	v_pk_fma_f32 v[166:167], v[100:101], v[100:101], v[166:167]
	v_pk_fma_f32 v[144:145], v[102:103], v[102:103], v[144:145]
	v_pk_fma_f32 v[166:167], v[96:97], v[96:97], v[166:167]
	v_pk_fma_f32 v[144:145], v[98:99], v[98:99], v[144:145]
	s_nop 0
	v_pk_add_f32 v[166:167], v[166:167], v[144:145]
	s_add_u32 s48, s18, 0x48000
	s_addc_u32 s49, s19, 0
	v_cvt_pk_bf16_f32 v108, v108, v109
	v_cvt_pk_bf16_f32 v109, v110, v111
	v_cvt_pk_bf16_f32 v104, v104, v105
	v_cvt_pk_bf16_f32 v105, v106, v107
	v_cvt_pk_bf16_f32 v100, v100, v101
	v_cvt_pk_bf16_f32 v101, v102, v103
	v_cvt_pk_bf16_f32 v96, v96, v97
	v_cvt_pk_bf16_f32 v97, v98, v99
	v_add_f32_e32 v218, v166, v167
	global_store_dwordx2 v131, v[108:109], s[48:49] sc1
	global_store_dwordx2 v131, v[104:105], s[48:49] offset:32 sc1
	global_store_dwordx2 v131, v[100:101], s[48:49] offset:256 sc1
	global_store_dwordx2 v131, v[96:97], s[48:49] offset:288 sc1
	v_mov_b32_e32 v219, v218
	s_nop 1
	v_permlane16_swap_b32_e32 v219, v218
	v_add_f32_e32 v218, v218, v219
	v_mov_b32_e32 v219, v218
	s_nop 1
	v_permlane32_swap_b32_e32 v219, v218
	v_add_f32_e32 v218, v218, v219
	s_and_saveexec_b64 s[0:1], s[40:41]
	global_atomic_add_f32 v130, v218, s[58:59] offset:576
	s_mov_b64 exec, s[0:1]
	s_waitcnt vmcnt(34)
	v_pk_add_f32 v[92:93], v[28:29], v[92:93]
	v_pk_add_f32 v[94:95], v[30:31], v[94:95]
	v_pk_add_f32 v[88:89], v[24:25], v[88:89]
	v_pk_add_f32 v[90:91], v[26:27], v[90:91]
	v_pk_add_f32 v[84:85], v[20:21], v[84:85]
	v_pk_add_f32 v[86:87], v[22:23], v[86:87]
	v_pk_add_f32 v[80:81], v[16:17], v[80:81]
	v_pk_add_f32 v[82:83], v[18:19], v[82:83]
	v_pk_mul_f32 v[166:167], v[92:93], v[92:93]
	v_pk_mul_f32 v[144:145], v[94:95], v[94:95]
	v_pk_fma_f32 v[166:167], v[88:89], v[88:89], v[166:167]
	v_pk_fma_f32 v[144:145], v[90:91], v[90:91], v[144:145]
	v_pk_fma_f32 v[166:167], v[84:85], v[84:85], v[166:167]
	v_pk_fma_f32 v[144:145], v[86:87], v[86:87], v[144:145]
	v_pk_fma_f32 v[166:167], v[80:81], v[80:81], v[166:167]
	v_pk_fma_f32 v[144:145], v[82:83], v[82:83], v[144:145]
	s_nop 0
	v_pk_add_f32 v[166:167], v[166:167], v[144:145]
	s_add_u32 s48, s18, 0x50000
	s_addc_u32 s49, s19, 0
	v_cvt_pk_bf16_f32 v92, v92, v93
	v_cvt_pk_bf16_f32 v93, v94, v95
	v_cvt_pk_bf16_f32 v88, v88, v89
	v_cvt_pk_bf16_f32 v89, v90, v91
	v_cvt_pk_bf16_f32 v84, v84, v85
	v_cvt_pk_bf16_f32 v85, v86, v87
	v_cvt_pk_bf16_f32 v80, v80, v81
	v_cvt_pk_bf16_f32 v81, v82, v83
	v_add_f32_e32 v218, v166, v167
	global_store_dwordx2 v131, v[92:93], s[48:49] sc1
	global_store_dwordx2 v131, v[88:89], s[48:49] offset:32 sc1
	global_store_dwordx2 v131, v[84:85], s[48:49] offset:256 sc1
	global_store_dwordx2 v131, v[80:81], s[48:49] offset:288 sc1
	v_mov_b32_e32 v219, v218
	s_nop 1
	v_permlane16_swap_b32_e32 v219, v218
	v_add_f32_e32 v218, v218, v219
	v_mov_b32_e32 v219, v218
	s_nop 1
	v_permlane32_swap_b32_e32 v219, v218
	v_add_f32_e32 v218, v218, v219
	s_and_saveexec_b64 s[0:1], s[40:41]
	global_atomic_add_f32 v130, v218, s[58:59] offset:640
	s_mov_b64 exec, s[0:1]
	s_waitcnt vmcnt(35)
	v_pk_add_f32 v[76:77], v[12:13], v[76:77]
	v_pk_add_f32 v[78:79], v[14:15], v[78:79]
	v_pk_add_f32 v[72:73], v[8:9], v[72:73]
	v_pk_add_f32 v[74:75], v[10:11], v[74:75]
	v_pk_add_f32 v[68:69], v[4:5], v[68:69]
	v_pk_add_f32 v[70:71], v[6:7], v[70:71]
	v_pk_add_f32 v[64:65], v[0:1], v[64:65]
	v_pk_add_f32 v[66:67], v[2:3], v[66:67]
	v_pk_mul_f32 v[166:167], v[76:77], v[76:77]
	v_pk_mul_f32 v[144:145], v[78:79], v[78:79]
	v_pk_fma_f32 v[166:167], v[72:73], v[72:73], v[166:167]
	v_pk_fma_f32 v[144:145], v[74:75], v[74:75], v[144:145]
	v_pk_fma_f32 v[166:167], v[68:69], v[68:69], v[166:167]
	v_pk_fma_f32 v[144:145], v[70:71], v[70:71], v[144:145]
	v_pk_fma_f32 v[166:167], v[64:65], v[64:65], v[166:167]
	v_pk_fma_f32 v[144:145], v[66:67], v[66:67], v[144:145]
	s_nop 0
	v_pk_add_f32 v[166:167], v[166:167], v[144:145]
	s_add_u32 s48, s18, 0x58000
	s_addc_u32 s49, s19, 0
	v_cvt_pk_bf16_f32 v76, v76, v77
	v_cvt_pk_bf16_f32 v77, v78, v79
	v_cvt_pk_bf16_f32 v72, v72, v73
	v_cvt_pk_bf16_f32 v73, v74, v75
	v_cvt_pk_bf16_f32 v68, v68, v69
	v_cvt_pk_bf16_f32 v69, v70, v71
	v_cvt_pk_bf16_f32 v64, v64, v65
	v_cvt_pk_bf16_f32 v65, v66, v67
	v_add_f32_e32 v218, v166, v167
	global_store_dwordx2 v131, v[76:77], s[48:49] sc1
	global_store_dwordx2 v131, v[72:73], s[48:49] offset:32 sc1
	global_store_dwordx2 v131, v[68:69], s[48:49] offset:256 sc1
	global_store_dwordx2 v131, v[64:65], s[48:49] offset:288 sc1
	v_mov_b32_e32 v219, v218
	s_nop 1
	v_permlane16_swap_b32_e32 v219, v218
	v_add_f32_e32 v218, v218, v219
	v_mov_b32_e32 v219, v218
	s_nop 1
	v_permlane32_swap_b32_e32 v219, v218
	v_add_f32_e32 v218, v218, v219
	s_and_saveexec_b64 s[0:1], s[40:41]
	global_atomic_add_f32 v130, v218, s[58:59] offset:704
	s_mov_b64 exec, s[0:1]
	s_cmp_eq_u32 s30, s28
	s_mov_b64 s[0:1], -1
	s_cbranch_scc1 .LBB0_955
